# EpiMix epilogue: z_pool loads prefetched 7 deep (rolling) instead of load-wait-store ladder; plus ynorm unroll
# speedup vs baseline: 1.0123x; 1.0123x over previous
.LBB0_600:
	ds_read_b128 v[128:131], v188
	ds_read_b128 v[132:135], v188 offset:1024
	ds_read_b128 v[136:139], v188 offset:2048
	ds_read_b128 v[140:143], v188 offset:3072
	s_add_u32 s30, s6, 0xfff80080
	s_addc_u32 s31, s7, -1
	s_cmp_eq_u32 s51, 4
	s_cselect_b32 s35, s25, s31
	s_cselect_b32 s34, s24, s30
	s_cselect_b32 s31, s2, s15
	s_cselect_b32 s30, s3, s13
	v_lshl_add_u64 v[202:203], s[6:7], 0, v[160:161]
	s_add_i32 m0, s29, 0xc000
	ds_read_b128 v[144:147], v189
	ds_read_b128 v[148:151], v189 offset:1024
	ds_read_b128 v[168:171], v189 offset:2048
	ds_read_b128 v[172:175], v189 offset:3072
	ds_read_b128 v[176:179], v189 offset:4096
	ds_read_b128 v[180:183], v189 offset:5120
	ds_read_b128 v[194:197], v189 offset:6144
	ds_read_b128 v[198:201], v189 offset:7168
	global_load_lds_dwordx4 v[202:203], off
	v_lshl_add_u64 v[202:203], s[6:7], 0, v[162:163]
	s_add_i32 m0, s29, 0xe000
	s_nop 0
	global_load_lds_dwordx4 v[202:203], off
	s_waitcnt lgkmcnt(8)
	s_barrier
	s_waitcnt lgkmcnt(0)
	s_setprio 1
	s_waitcnt lgkmcnt(0)
	v_mfma_f32_16x16x32_bf16 v[124:127], v[128:131], v[144:147], v[124:127]
	v_mfma_f32_16x16x32_bf16 v[120:123], v[136:139], v[144:147], v[120:123]
	v_mfma_f32_16x16x32_bf16 v[116:119], v[128:131], v[168:171], v[116:119]
	v_mfma_f32_16x16x32_bf16 v[112:115], v[136:139], v[168:171], v[112:115]
	v_mfma_f32_16x16x32_bf16 v[108:111], v[128:131], v[176:179], v[108:111]
	v_mfma_f32_16x16x32_bf16 v[104:107], v[136:139], v[176:179], v[104:107]
	v_mfma_f32_16x16x32_bf16 v[100:103], v[128:131], v[194:197], v[100:103]
	v_mfma_f32_16x16x32_bf16 v[96:99], v[136:139], v[194:197], v[96:99]
	v_mfma_f32_16x16x32_bf16 v[124:127], v[132:135], v[148:151], v[124:127]
	v_mfma_f32_16x16x32_bf16 v[120:123], v[140:143], v[148:151], v[120:123]
	v_mfma_f32_16x16x32_bf16 v[116:119], v[132:135], v[172:175], v[116:119]
	v_mfma_f32_16x16x32_bf16 v[112:115], v[140:143], v[172:175], v[112:115]
	v_mfma_f32_16x16x32_bf16 v[108:111], v[132:135], v[180:183], v[108:111]
	v_mfma_f32_16x16x32_bf16 v[104:107], v[140:143], v[180:183], v[104:107]
	v_mfma_f32_16x16x32_bf16 v[100:103], v[132:135], v[198:201], v[100:103]
	v_mfma_f32_16x16x32_bf16 v[96:99], v[140:143], v[198:201], v[96:99]
	s_setprio 0
	s_barrier
	s_add_i32 s52, s47, s38
	v_lshl_add_u64 v[218:219], s[30:31], 0, v[156:157]
	s_mov_b32 m0, s52
	ds_read_b128 v[202:205], v190
	ds_read_b128 v[206:209], v190 offset:1024
	ds_read_b128 v[210:213], v190 offset:2048
	ds_read_b128 v[214:217], v190 offset:3072
	global_load_lds_dwordx4 v[218:219], off
	v_lshl_add_u64 v[220:221], s[30:31], 0, v[152:153]
	s_add_i32 m0, s52, 0x2000
	s_nop 0
	global_load_lds_dwordx4 v[220:221], off
	s_barrier
	s_waitcnt lgkmcnt(0)
	s_setprio 1
	s_waitcnt lgkmcnt(0)
	v_mfma_f32_16x16x32_bf16 v[60:63], v[202:205], v[144:147], v[60:63]
	v_mfma_f32_16x16x32_bf16 v[56:59], v[210:213], v[144:147], v[56:59]
	v_mfma_f32_16x16x32_bf16 v[52:55], v[202:205], v[168:171], v[52:55]
	v_mfma_f32_16x16x32_bf16 v[48:51], v[210:213], v[168:171], v[48:51]
	v_mfma_f32_16x16x32_bf16 v[44:47], v[202:205], v[176:179], v[44:47]
	v_mfma_f32_16x16x32_bf16 v[40:43], v[210:213], v[176:179], v[40:43]
	v_mfma_f32_16x16x32_bf16 v[36:39], v[202:205], v[194:197], v[36:39]
	v_mfma_f32_16x16x32_bf16 v[32:35], v[210:213], v[194:197], v[32:35]
	v_mfma_f32_16x16x32_bf16 v[60:63], v[206:209], v[148:151], v[60:63]
	v_mfma_f32_16x16x32_bf16 v[56:59], v[214:217], v[148:151], v[56:59]
	v_mfma_f32_16x16x32_bf16 v[52:55], v[206:209], v[172:175], v[52:55]
	v_mfma_f32_16x16x32_bf16 v[48:51], v[214:217], v[172:175], v[48:51]
	v_mfma_f32_16x16x32_bf16 v[44:47], v[206:209], v[180:183], v[44:47]
	v_mfma_f32_16x16x32_bf16 v[40:43], v[214:217], v[180:183], v[40:43]
	v_mfma_f32_16x16x32_bf16 v[36:39], v[206:209], v[198:201], v[36:39]
	v_mfma_f32_16x16x32_bf16 v[32:35], v[214:217], v[198:201], v[32:35]
	s_setprio 0
	s_mov_b32 m0, s29
	v_lshl_add_u64 v[222:223], s[34:35], 0, v[158:159]
	s_barrier
	ds_read_b128 v[144:147], v189 offset:16384
	ds_read_b128 v[148:151], v189 offset:17408
	ds_read_b128 v[168:171], v189 offset:18432
	ds_read_b128 v[172:175], v189 offset:19456
	ds_read_b128 v[176:179], v189 offset:20480
	ds_read_b128 v[180:183], v189 offset:21504
	ds_read_b128 v[194:197], v189 offset:22528
	ds_read_b128 v[198:201], v189 offset:23552
	global_load_lds_dwordx4 v[222:223], off
	v_lshl_add_u64 v[224:225], s[34:35], 0, v[154:155]
	s_mov_b32 m0, s39
	s_nop 0
	global_load_lds_dwordx4 v[224:225], off
	s_barrier
	s_waitcnt lgkmcnt(0)
	s_setprio 1
	s_waitcnt lgkmcnt(0)
	v_mfma_f32_16x16x32_bf16 v[92:95], v[128:131], v[144:147], v[92:95]
	v_mfma_f32_16x16x32_bf16 v[88:91], v[136:139], v[144:147], v[88:91]
	v_mfma_f32_16x16x32_bf16 v[84:87], v[128:131], v[168:171], v[84:87]
	v_mfma_f32_16x16x32_bf16 v[80:83], v[136:139], v[168:171], v[80:83]
	v_mfma_f32_16x16x32_bf16 v[76:79], v[128:131], v[176:179], v[76:79]
	v_mfma_f32_16x16x32_bf16 v[72:75], v[136:139], v[176:179], v[72:75]
	v_mfma_f32_16x16x32_bf16 v[68:71], v[128:131], v[194:197], v[68:71]
	v_mfma_f32_16x16x32_bf16 v[64:67], v[136:139], v[194:197], v[64:67]
	v_mfma_f32_16x16x32_bf16 v[92:95], v[132:135], v[148:151], v[92:95]
	v_mfma_f32_16x16x32_bf16 v[88:91], v[140:143], v[148:151], v[88:91]
	v_mfma_f32_16x16x32_bf16 v[84:87], v[132:135], v[172:175], v[84:87]
	v_mfma_f32_16x16x32_bf16 v[80:83], v[140:143], v[172:175], v[80:83]
	v_mfma_f32_16x16x32_bf16 v[76:79], v[132:135], v[180:183], v[76:79]
	v_mfma_f32_16x16x32_bf16 v[72:75], v[140:143], v[180:183], v[72:75]
	v_mfma_f32_16x16x32_bf16 v[68:71], v[132:135], v[198:201], v[68:71]
	v_mfma_f32_16x16x32_bf16 v[64:67], v[140:143], v[198:201], v[64:67]
	s_setprio 0
	s_barrier
	s_add_u32 s52, s30, 0x20000
	s_addc_u32 s53, s31, 0
	s_add_i32 s54, s48, s38
	v_lshl_add_u64 v[128:129], s[52:53], 0, v[156:157]
	s_mov_b32 m0, s54
	s_nop 0
	global_load_lds_dwordx4 v[128:129], off
	v_lshl_add_u64 v[128:129], s[52:53], 0, v[152:153]
	s_add_i32 m0, s54, 0x2000
	s_nop 0
	global_load_lds_dwordx4 v[128:129], off
	s_waitcnt vmcnt(6)
	s_barrier
	s_setprio 1
	v_mfma_f32_16x16x32_bf16 v[28:31], v[202:205], v[144:147], v[28:31]
	v_mfma_f32_16x16x32_bf16 v[24:27], v[210:213], v[144:147], v[24:27]
	v_mfma_f32_16x16x32_bf16 v[20:23], v[202:205], v[168:171], v[20:23]
	v_mfma_f32_16x16x32_bf16 v[16:19], v[210:213], v[168:171], v[16:19]
	v_mfma_f32_16x16x32_bf16 v[12:15], v[202:205], v[176:179], v[12:15]
	v_mfma_f32_16x16x32_bf16 v[8:11], v[210:213], v[176:179], v[8:11]
	v_mfma_f32_16x16x32_bf16 v[4:7], v[202:205], v[194:197], v[4:7]
	v_mfma_f32_16x16x32_bf16 v[0:3], v[210:213], v[194:197], v[0:3]
	v_mfma_f32_16x16x32_bf16 v[28:31], v[206:209], v[148:151], v[28:31]
	v_mfma_f32_16x16x32_bf16 v[24:27], v[214:217], v[148:151], v[24:27]
	v_mfma_f32_16x16x32_bf16 v[20:23], v[206:209], v[172:175], v[20:23]
	v_mfma_f32_16x16x32_bf16 v[16:19], v[214:217], v[172:175], v[16:19]
	v_mfma_f32_16x16x32_bf16 v[12:15], v[206:209], v[180:183], v[12:15]
	v_mfma_f32_16x16x32_bf16 v[8:11], v[214:217], v[180:183], v[8:11]
	v_mfma_f32_16x16x32_bf16 v[4:7], v[206:209], v[198:201], v[4:7]
	v_mfma_f32_16x16x32_bf16 v[0:3], v[214:217], v[198:201], v[0:3]
	s_setprio 0
	s_add_i32 s52, 0, 0x18000
	v_add_u32_e32 v140, s52, v186
	s_barrier
	ds_read_b128 v[128:131], v140
	ds_read_b128 v[132:135], v140 offset:1024
	ds_read_b128 v[136:139], v140 offset:2048
	ds_read_b128 v[140:143], v140 offset:3072
	s_add_u32 s34, s34, 0x80000
	s_addc_u32 s35, s35, 0
	s_mov_b32 m0, s40
	v_lshl_add_u64 v[202:203], s[34:35], 0, v[158:159]
	ds_read_b128 v[144:147], v189 offset:32768
	ds_read_b128 v[148:151], v189 offset:33792
	ds_read_b128 v[168:171], v189 offset:34816
	ds_read_b128 v[172:175], v189 offset:35840
	ds_read_b128 v[176:179], v189 offset:36864
	ds_read_b128 v[180:183], v189 offset:37888
	ds_read_b128 v[194:197], v189 offset:38912
	ds_read_b128 v[198:201], v189 offset:39936
	global_load_lds_dwordx4 v[202:203], off
	v_lshl_add_u64 v[202:203], s[34:35], 0, v[154:155]
	s_mov_b32 m0, s41
	s_nop 0
	global_load_lds_dwordx4 v[202:203], off
	s_waitcnt lgkmcnt(8)
	s_barrier
	s_waitcnt lgkmcnt(0)
	s_setprio 1
	s_waitcnt lgkmcnt(0)
	v_mfma_f32_16x16x32_bf16 v[124:127], v[128:131], v[144:147], v[124:127]
	v_mfma_f32_16x16x32_bf16 v[120:123], v[136:139], v[144:147], v[120:123]
	v_mfma_f32_16x16x32_bf16 v[116:119], v[128:131], v[168:171], v[116:119]
	v_mfma_f32_16x16x32_bf16 v[112:115], v[136:139], v[168:171], v[112:115]
	v_mfma_f32_16x16x32_bf16 v[108:111], v[128:131], v[176:179], v[108:111]
	v_mfma_f32_16x16x32_bf16 v[104:107], v[136:139], v[176:179], v[104:107]
	v_mfma_f32_16x16x32_bf16 v[100:103], v[128:131], v[194:197], v[100:103]
	v_mfma_f32_16x16x32_bf16 v[96:99], v[136:139], v[194:197], v[96:99]
	v_mfma_f32_16x16x32_bf16 v[124:127], v[132:135], v[148:151], v[124:127]
	v_mfma_f32_16x16x32_bf16 v[120:123], v[140:143], v[148:151], v[120:123]
	v_mfma_f32_16x16x32_bf16 v[116:119], v[132:135], v[172:175], v[116:119]
	v_mfma_f32_16x16x32_bf16 v[112:115], v[140:143], v[172:175], v[112:115]
	v_mfma_f32_16x16x32_bf16 v[108:111], v[132:135], v[180:183], v[108:111]
	v_mfma_f32_16x16x32_bf16 v[104:107], v[140:143], v[180:183], v[104:107]
	v_mfma_f32_16x16x32_bf16 v[100:103], v[132:135], v[198:201], v[100:103]
	v_mfma_f32_16x16x32_bf16 v[96:99], v[140:143], v[198:201], v[96:99]
	s_setprio 0
	s_barrier
	s_add_i32 s34, 0, 0x1c000
	s_add_i32 s35, s52, s38
	v_add_u32_e32 v191, s34, v186
	v_lshl_add_u64 v[218:219], v[218:219], 0, s[0:1]
	s_mov_b32 m0, s35
	ds_read_b128 v[202:205], v191
	ds_read_b128 v[206:209], v191 offset:1024
	ds_read_b128 v[210:213], v191 offset:2048
	ds_read_b128 v[214:217], v191 offset:3072
	global_load_lds_dwordx4 v[218:219], off
	v_lshl_add_u64 v[218:219], v[220:221], 0, s[0:1]
	s_add_i32 m0, s35, 0x2000
	s_nop 0
	global_load_lds_dwordx4 v[218:219], off
	s_barrier
	s_waitcnt lgkmcnt(0)
	s_setprio 1
	s_waitcnt lgkmcnt(0)
	v_mfma_f32_16x16x32_bf16 v[60:63], v[202:205], v[144:147], v[60:63]
	v_mfma_f32_16x16x32_bf16 v[56:59], v[210:213], v[144:147], v[56:59]
	v_mfma_f32_16x16x32_bf16 v[52:55], v[202:205], v[168:171], v[52:55]
	v_mfma_f32_16x16x32_bf16 v[48:51], v[210:213], v[168:171], v[48:51]
	v_mfma_f32_16x16x32_bf16 v[44:47], v[202:205], v[176:179], v[44:47]
	v_mfma_f32_16x16x32_bf16 v[40:43], v[210:213], v[176:179], v[40:43]
	v_mfma_f32_16x16x32_bf16 v[36:39], v[202:205], v[194:197], v[36:39]
	v_mfma_f32_16x16x32_bf16 v[32:35], v[210:213], v[194:197], v[32:35]
	v_mfma_f32_16x16x32_bf16 v[60:63], v[206:209], v[148:151], v[60:63]
	v_mfma_f32_16x16x32_bf16 v[56:59], v[214:217], v[148:151], v[56:59]
	v_mfma_f32_16x16x32_bf16 v[52:55], v[206:209], v[172:175], v[52:55]
	v_mfma_f32_16x16x32_bf16 v[48:51], v[214:217], v[172:175], v[48:51]
	v_mfma_f32_16x16x32_bf16 v[44:47], v[206:209], v[180:183], v[44:47]
	v_mfma_f32_16x16x32_bf16 v[40:43], v[214:217], v[180:183], v[40:43]
	v_mfma_f32_16x16x32_bf16 v[36:39], v[206:209], v[198:201], v[36:39]
	v_mfma_f32_16x16x32_bf16 v[32:35], v[214:217], v[198:201], v[32:35]
	s_setprio 0
	s_mov_b32 m0, s43
	v_lshl_add_u64 v[218:219], v[222:223], 0, s[0:1]
	s_barrier
	ds_read_b128 v[144:147], v189 offset:49152
	ds_read_b128 v[148:151], v189 offset:50176
	ds_read_b128 v[168:171], v189 offset:51200
	ds_read_b128 v[172:175], v189 offset:52224
	ds_read_b128 v[176:179], v189 offset:53248
	ds_read_b128 v[180:183], v189 offset:54272
	ds_read_b128 v[194:197], v189 offset:55296
	ds_read_b128 v[198:201], v189 offset:56320
	global_load_lds_dwordx4 v[218:219], off
	v_lshl_add_u64 v[218:219], v[224:225], 0, s[0:1]
	s_mov_b32 m0, s44
	s_nop 0
	global_load_lds_dwordx4 v[218:219], off
	s_barrier
; template <class Epi>
; __device__ __forceinline__ void gemm_phase(LAS unsigned char* lds, const GemmD g, const Epi& E) {
;     ...
;         for (int t = 0; t < nt; t += 2) PG8_KITER(t);
;     __device__ __forceinline__ void operator()(const f32x4 (&acc)[2][2][4][2], const Unit& u, int wr, int wc, int fr, int fq) const {
;         const int row0 = u.pm * BM + wr * 64 + fr, col0 = u.pn * BM + wc * 32 + 8 * fq;
; #pragma unroll
;         for (int bj = 0; bj < 2; ++bj) { const int col = col0 + bj * HALF;
;             const f32x4 b0 = *(const f32x4*)(bias + col), b1 = *(const f32x4*)(bias + col + 4), s0 = *(const f32x4*)(scale + col), s1 = *(const f32x4*)(scale + col + 4);
; #pragma unroll
;             for (int ai = 0; ai < 2; ++ai)
; #pragma unroll
;                 for (int m = 0; m < 4; ++m) { const int row = row0 + ai * HALF + m * 16;
;                     const u32x4 z = __builtin_nontemporal_load((const u32x4*)(proj + (size_t)row * NPROJ + C_ZP + col));
;                     f32x4 v0 = (acc[ai][bj][m][0] + b0) * s0, v1 = (acc[ai][bj][m][1] + b1) * s1;
	s_waitcnt lgkmcnt(0)
	s_setprio 1
	s_waitcnt lgkmcnt(0)
	v_mfma_f32_16x16x32_bf16 v[92:95], v[128:131], v[144:147], v[92:95]
	v_mfma_f32_16x16x32_bf16 v[88:91], v[136:139], v[144:147], v[88:91]
	v_mfma_f32_16x16x32_bf16 v[84:87], v[128:131], v[168:171], v[84:87]
	v_mfma_f32_16x16x32_bf16 v[80:83], v[136:139], v[168:171], v[80:83]
	v_mfma_f32_16x16x32_bf16 v[76:79], v[128:131], v[176:179], v[76:79]
	v_mfma_f32_16x16x32_bf16 v[72:75], v[136:139], v[176:179], v[72:75]
	v_mfma_f32_16x16x32_bf16 v[68:71], v[128:131], v[194:197], v[68:71]
	v_mfma_f32_16x16x32_bf16 v[64:67], v[136:139], v[194:197], v[64:67]
	v_mfma_f32_16x16x32_bf16 v[92:95], v[132:135], v[148:151], v[92:95]
	v_mfma_f32_16x16x32_bf16 v[88:91], v[140:143], v[148:151], v[88:91]
	v_mfma_f32_16x16x32_bf16 v[84:87], v[132:135], v[172:175], v[84:87]
	v_mfma_f32_16x16x32_bf16 v[80:83], v[140:143], v[172:175], v[80:83]
	v_mfma_f32_16x16x32_bf16 v[76:79], v[132:135], v[180:183], v[76:79]
	v_mfma_f32_16x16x32_bf16 v[72:75], v[140:143], v[180:183], v[72:75]
	v_mfma_f32_16x16x32_bf16 v[68:71], v[132:135], v[198:201], v[68:71]
	v_mfma_f32_16x16x32_bf16 v[64:67], v[140:143], v[198:201], v[64:67]
	s_setprio 0
	s_barrier
	s_add_u32 s30, s30, 0x20080
	s_addc_u32 s31, s31, 0
	s_add_i32 s34, s34, s38
	v_lshl_add_u64 v[128:129], s[30:31], 0, v[156:157]
	s_mov_b32 m0, s34
	s_nop 0
	global_load_lds_dwordx4 v[128:129], off
	v_lshl_add_u64 v[128:129], s[30:31], 0, v[152:153]
	s_add_i32 m0, s34, 0x2000
	s_nop 0
	global_load_lds_dwordx4 v[128:129], off
	s_waitcnt vmcnt(6)
	s_barrier
	s_setprio 1
	v_mfma_f32_16x16x32_bf16 v[28:31], v[202:205], v[144:147], v[28:31]
	v_mfma_f32_16x16x32_bf16 v[24:27], v[210:213], v[144:147], v[24:27]
	v_mfma_f32_16x16x32_bf16 v[20:23], v[202:205], v[168:171], v[20:23]
	v_mfma_f32_16x16x32_bf16 v[16:19], v[210:213], v[168:171], v[16:19]
	v_mfma_f32_16x16x32_bf16 v[12:15], v[202:205], v[176:179], v[12:15]
	v_mfma_f32_16x16x32_bf16 v[8:11], v[210:213], v[176:179], v[8:11]
	v_mfma_f32_16x16x32_bf16 v[4:7], v[202:205], v[194:197], v[4:7]
	v_mfma_f32_16x16x32_bf16 v[0:3], v[210:213], v[194:197], v[0:3]
	v_mfma_f32_16x16x32_bf16 v[28:31], v[206:209], v[148:151], v[28:31]
	v_mfma_f32_16x16x32_bf16 v[24:27], v[214:217], v[148:151], v[24:27]
	v_mfma_f32_16x16x32_bf16 v[20:23], v[206:209], v[172:175], v[20:23]
	v_mfma_f32_16x16x32_bf16 v[16:19], v[214:217], v[172:175], v[16:19]
	v_mfma_f32_16x16x32_bf16 v[12:15], v[206:209], v[180:183], v[12:15]
	v_mfma_f32_16x16x32_bf16 v[8:11], v[214:217], v[180:183], v[8:11]
	v_mfma_f32_16x16x32_bf16 v[4:7], v[206:209], v[198:201], v[4:7]
	v_mfma_f32_16x16x32_bf16 v[0:3], v[214:217], v[198:201], v[0:3]
	s_setprio 0
	s_add_i32 s51, s51, 2
	s_add_u32 s6, s6, 0x100
	s_addc_u32 s7, s7, 0
	s_add_u32 s13, s13, 0x100
	s_addc_u32 s15, s15, 0
	s_cmp_gt_u32 s51, 5
	s_barrier
	s_cbranch_scc0 .LBB0_600
	v_lshl_add_u32 v176, s28, 8, v185
	v_lshl_or_b32 v148, s50, 8, v187
	v_mov_b64_e32 v[178:179], s[92:93]
	v_ashrrev_i32_e32 v149, 31, v148
	v_readlane_b32 s52, v244, 0
	v_mad_i64_i32 v[138:139], s[2:3], v176, s49, v[178:179]
	v_lshlrev_b64 v[136:137], 2, v[148:149]
	v_readlane_b32 s53, v244, 1
	v_lshl_add_u64 v[150:151], v[138:139], 0, s[8:9]
	v_lshlrev_b64 v[174:175], 1, v[148:149]
	v_lshl_add_u64 v[170:171], s[52:53], 0, v[136:137]
	v_lshl_add_u64 v[138:139], v[150:151], 0, v[174:175]
	global_load_dwordx4 v[128:131], v[170:171], off offset:16
	global_load_dwordx4 v[132:135], v[170:171], off
	v_mov_b32_e32 v254, v138
	v_mov_b32_e32 v255, v139
	global_load_dwordx4 v[144:147], v[138:139], off nt
	v_readlane_b32 s54, v244, 2
	v_readlane_b32 s55, v244, 3
	v_ashrrev_i32_e32 v177, 31, v176
	v_lshlrev_b64 v[168:169], 13, v[176:177]
	v_lshl_add_u64 v[172:173], s[54:55], 0, v[136:137]
	global_load_dwordx4 v[140:143], v[172:173], off
	global_load_dwordx4 v[136:139], v[172:173], off offset:16
	v_readlane_b32 s6, v244, 45
	v_readlane_b32 s7, v244, 46
	v_or_b32_e32 v182, 16, v176
	v_mad_i64_i32 v[194:195], s[2:3], v182, s49, v[178:179]
	v_lshl_add_u64 v[180:181], s[6:7], 0, v[168:169]
	v_lshl_add_u64 v[180:181], v[180:181], 0, s[10:11]
	v_lshl_add_u64 v[196:197], v[180:181], 0, v[174:175]
	v_or_b32_e32 v148, 0x80, v148
	v_ashrrev_i32_e32 v149, 31, v148
	v_lshlrev_b64 v[168:169], 1, v[148:149]
	v_lshl_add_u64 v[148:149], v[150:151], 0, v[168:169]
	global_load_dwordx4 v[148:151], v[148:149], off nt
	s_mov_b32 s60, 0x6a000
	s_mov_b32 s61, 0
	v_lshl_add_u64 v[206:207], v[254:255], 0, s[60:61]
	global_load_dwordx4 v[206:209], v[206:207], off nt
	s_mov_b32 s60, 0xd4000
	s_mov_b32 s61, 0
	v_lshl_add_u64 v[210:211], v[254:255], 0, s[60:61]
	global_load_dwordx4 v[210:213], v[210:211], off nt
	s_mov_b32 s60, 0x13e000
	s_mov_b32 s61, 0
	v_lshl_add_u64 v[214:215], v[254:255], 0, s[60:61]
	global_load_dwordx4 v[214:217], v[214:215], off nt
	s_mov_b32 s60, 0x350000
	s_mov_b32 s61, 0
	v_lshl_add_u64 v[218:219], v[254:255], 0, s[60:61]
	global_load_dwordx4 v[218:221], v[218:219], off nt
	s_mov_b32 s60, 0x3ba000
	s_mov_b32 s61, 0
	v_lshl_add_u64 v[222:223], v[254:255], 0, s[60:61]
	global_load_dwordx4 v[222:225], v[222:223], off nt
	s_mov_b32 s60, 0x424000
	s_mov_b32 s61, 0
	v_lshl_add_u64 v[226:227], v[254:255], 0, s[60:61]
	global_load_dwordx4 v[226:229], v[226:227], off nt
	s_mov_b32 s60, 0x48e000
	s_mov_b32 s61, 0
	v_lshl_add_u64 v[230:231], v[254:255], 0, s[60:61]
	global_load_dwordx4 v[230:233], v[230:231], off nt
	s_and_b64 vcc, exec, s[4:5]
	s_mov_b32 s50, s12
	s_mov_b32 s28, s14
	s_mov_b64 s[30:31], s[26:27]
	s_mov_b64 s[34:35], s[24:25]
	v_readlane_b32 s56, v244, 4
	v_readlane_b32 s57, v244, 5
	v_readlane_b32 s58, v244, 6
	v_readlane_b32 s59, v244, 7
	s_waitcnt vmcnt(8)
; __device__ __forceinline__ float bflo(unsigned w) { return __uint_as_float(w << 16); }
; __device__ __forceinline__ float bfhi(unsigned w) { return __uint_as_float(w & 0xffff0000u); }
; __device__ __forceinline__ unsigned pk2(float lo, float hi) { unsigned r; asm("v_cvt_pk_bf16_f32 %0, %1, %2" : "=v"(r) : "v"(lo), "v"(hi)); return r; }
; __device__ __forceinline__ float siluf_(float x) { return x * __builtin_amdgcn_rcpf(1.0f + __expf(-x)); }
;     __device__ __forceinline__ void operator()(const f32x4 (&acc)[2][2][4][2], const Unit& u, int wr, int wc, int fr, int fq) const {
;     ...
;             for (int ai = 0; ai < 2; ++ai)
; #pragma unroll
;                 for (int m = 0; m < 4; ++m) { const int row = row0 + ai * HALF + m * 16;
;                     const u32x4 z = __builtin_nontemporal_load((const u32x4*)(proj + (size_t)row * NPROJ + C_ZP + col));
;                     f32x4 v0 = (acc[ai][bj][m][0] + b0) * s0, v1 = (acc[ai][bj][m][1] + b1) * s1;
;                     v0[0] *= siluf_(bflo(z.x)); v0[1] *= siluf_(bfhi(z.x)); v0[2] *= siluf_(bflo(z.y)); v0[3] *= siluf_(bfhi(z.y));
;                     v1[0] *= siluf_(bflo(z.z)); v1[1] *= siluf_(bfhi(z.z)); v1[2] *= siluf_(bflo(z.w)); v1[3] *= siluf_(bfhi(z.w));
;                     u32x4 w; w.x = pk2(v0[0], v0[1]); w.y = pk2(v0[2], v0[3]); w.z = pk2(v1[0], v1[1]); w.w = pk2(v1[2], v1[3]);
;                     *(u32x4*)(a2 + (size_t)row * 4096 + 2048 + col) = w; } }
	v_pk_add_f32 v[122:123], v[122:123], v[130:131]
	v_pk_add_f32 v[124:125], v[124:125], v[132:133]
	v_lshlrev_b32_e32 v177, 16, v144
	v_and_b32_e32 v144, 0xffff0000, v144
	v_lshlrev_b32_e32 v183, 16, v145
	v_and_b32_e32 v145, 0xffff0000, v145
	v_lshlrev_b32_e32 v191, 16, v146
	v_and_b32_e32 v146, 0xffff0000, v146
	v_lshlrev_b32_e32 v193, 16, v147
	v_and_b32_e32 v147, 0xffff0000, v147
	v_mul_f32_e32 v198, 0xbfb8aa3b, v177
	v_mul_f32_e32 v199, 0xbfb8aa3b, v144
	v_mul_f32_e32 v200, 0xbfb8aa3b, v183
	v_mul_f32_e32 v201, 0xbfb8aa3b, v145
	v_mul_f32_e32 v202, 0xbfb8aa3b, v191
	v_mul_f32_e32 v203, 0xbfb8aa3b, v146
	v_mul_f32_e32 v205, 0xbfb8aa3b, v147
	v_exp_f32_e32 v198, v198
	v_exp_f32_e32 v199, v199
	v_mul_f32_e32 v204, 0xbfb8aa3b, v193
	v_exp_f32_e32 v200, v200
	v_exp_f32_e32 v201, v201
	v_exp_f32_e32 v202, v202
	v_exp_f32_e32 v203, v203
	v_exp_f32_e32 v205, v205
	v_exp_f32_e32 v204, v204
	v_add_f32_e32 v198, 1.0, v198
	v_add_f32_e32 v199, 1.0, v199
	v_add_f32_e32 v200, 1.0, v200
	v_add_f32_e32 v201, 1.0, v201
	v_add_f32_e32 v202, 1.0, v202
	v_add_f32_e32 v203, 1.0, v203
	v_add_f32_e32 v205, 1.0, v205
	v_rcp_f32_e32 v198, v198
	v_rcp_f32_e32 v199, v199
	v_add_f32_e32 v204, 1.0, v204
	v_rcp_f32_e32 v200, v200
	v_rcp_f32_e32 v201, v201
	v_rcp_f32_e32 v202, v202
	v_rcp_f32_e32 v203, v203
	v_rcp_f32_e32 v205, v205
	v_rcp_f32_e32 v204, v204
	v_pk_add_f32 v[126:127], v[126:127], v[134:135]
	v_pk_add_f32 v[120:121], v[120:121], v[128:129]
	v_pk_mul_f32 v[124:125], v[124:125], v[140:141]
	v_mul_f32_e32 v177, v198, v177
	v_mul_f32_e32 v144, v199, v144
	v_pk_mul_f32 v[126:127], v[126:127], v[142:143]
	v_pk_mul_f32 v[122:123], v[122:123], v[138:139]
	v_pk_mul_f32 v[120:121], v[120:121], v[136:137]
	v_mul_f32_e32 v183, v200, v183
	v_mul_f32_e32 v145, v201, v145
	v_mul_f32_e32 v191, v202, v191
	v_mul_f32_e32 v146, v203, v146
	v_mul_f32_e32 v147, v205, v147
	v_mul_f32_e32 v124, v124, v177
	v_mul_f32_e32 v125, v125, v144
	v_mul_f32_e32 v193, v204, v193
	v_mul_f32_e32 v126, v126, v183
	v_mul_f32_e32 v127, v127, v145
	v_mul_f32_e32 v144, v120, v191
	v_mul_f32_e32 v145, v121, v146
	v_mul_f32_e32 v123, v123, v147
	v_cvt_pk_bf16_f32 v120, v124, v125
	v_cvt_pk_bf16_f32 v121, v126, v127
	v_lshl_add_u64 v[124:125], v[194:195], 0, s[8:9]
	v_mul_f32_e32 v146, v122, v193
	v_cvt_pk_bf16_f32 v122, v144, v145
	v_cvt_pk_bf16_f32 v123, v146, v123
	global_store_dwordx4 v[196:197], v[120:123], off
	v_ashrrev_i32_e32 v183, 31, v182
	v_or_b32_e32 v126, 32, v176
	v_lshl_add_u64 v[120:121], v[124:125], 0, v[174:175]
	v_lshlrev_b64 v[122:123], 13, v[182:183]
	v_lshl_add_u64 v[122:123], s[6:7], 0, v[122:123]
	v_pk_add_f32 v[114:115], v[114:115], v[130:131]
	v_mad_i64_i32 v[120:121], s[2:3], v126, s49, v[178:179]
	v_lshl_add_u64 v[122:123], v[122:123], 0, s[10:11]
	v_pk_add_f32 v[118:119], v[118:119], v[134:135]
	v_pk_add_f32 v[116:117], v[116:117], v[132:133]
	v_pk_add_f32 v[112:113], v[112:113], v[128:129]
	v_pk_mul_f32 v[114:115], v[114:115], v[138:139]
	v_lshl_add_u64 v[120:121], v[120:121], 0, s[8:9]
	v_lshl_add_u64 v[194:195], v[122:123], 0, v[174:175]
	v_pk_mul_f32 v[118:119], v[118:119], v[142:143]
	v_pk_mul_f32 v[116:117], v[116:117], v[140:141]
	v_pk_mul_f32 v[112:113], v[112:113], v[136:137]
	v_lshl_add_u64 v[182:183], v[120:121], 0, v[174:175]
	v_pk_add_f32 v[106:107], v[106:107], v[130:131]
	v_pk_add_f32 v[110:111], v[110:111], v[134:135]
	v_pk_add_f32 v[108:109], v[108:109], v[132:133]
	v_pk_add_f32 v[104:105], v[104:105], v[128:129]
	v_pk_mul_f32 v[106:107], v[106:107], v[138:139]
	v_pk_mul_f32 v[110:111], v[110:111], v[142:143]
	v_pk_mul_f32 v[108:109], v[108:109], v[140:141]
	v_pk_mul_f32 v[104:105], v[104:105], v[136:137]
	v_pk_add_f32 v[98:99], v[98:99], v[130:131]
	v_pk_add_f32 v[102:103], v[102:103], v[134:135]
	v_pk_add_f32 v[100:101], v[100:101], v[132:133]
	v_pk_add_f32 v[96:97], v[96:97], v[128:129]
	v_pk_mul_f32 v[98:99], v[98:99], v[138:139]
	v_pk_mul_f32 v[102:103], v[102:103], v[142:143]
	v_pk_mul_f32 v[100:101], v[100:101], v[140:141]
	v_pk_mul_f32 v[96:97], v[96:97], v[136:137]
	v_pk_add_f32 v[90:91], v[90:91], v[130:131]
	v_pk_add_f32 v[94:95], v[94:95], v[134:135]
	v_pk_add_f32 v[92:93], v[92:93], v[132:133]
	v_pk_add_f32 v[88:89], v[88:89], v[128:129]
	v_pk_mul_f32 v[90:91], v[90:91], v[138:139]
	v_pk_mul_f32 v[94:95], v[94:95], v[142:143]
	v_pk_mul_f32 v[92:93], v[92:93], v[140:141]
	v_pk_mul_f32 v[88:89], v[88:89], v[136:137]
	v_pk_add_f32 v[82:83], v[82:83], v[130:131]
	v_pk_add_f32 v[86:87], v[86:87], v[134:135]
	v_pk_add_f32 v[84:85], v[84:85], v[132:133]
	v_pk_add_f32 v[80:81], v[80:81], v[128:129]
	v_pk_mul_f32 v[82:83], v[82:83], v[138:139]
	v_pk_mul_f32 v[86:87], v[86:87], v[142:143]
	v_pk_mul_f32 v[84:85], v[84:85], v[140:141]
	v_pk_mul_f32 v[80:81], v[80:81], v[136:137]
	v_pk_add_f32 v[74:75], v[74:75], v[130:131]
	v_pk_add_f32 v[78:79], v[78:79], v[134:135]
	v_pk_add_f32 v[76:77], v[76:77], v[132:133]
	v_pk_add_f32 v[72:73], v[72:73], v[128:129]
	v_pk_mul_f32 v[74:75], v[74:75], v[138:139]
	v_pk_mul_f32 v[78:79], v[78:79], v[142:143]
	v_pk_mul_f32 v[76:77], v[76:77], v[140:141]
	v_pk_mul_f32 v[72:73], v[72:73], v[136:137]
	v_pk_add_f32 v[66:67], v[66:67], v[130:131]
	v_pk_add_f32 v[70:71], v[70:71], v[134:135]
	v_pk_add_f32 v[68:69], v[68:69], v[132:133]
	v_pk_add_f32 v[64:65], v[64:65], v[128:129]
	v_pk_mul_f32 v[66:67], v[66:67], v[138:139]
	v_pk_mul_f32 v[70:71], v[70:71], v[142:143]
	v_pk_mul_f32 v[68:69], v[68:69], v[140:141]
	v_pk_mul_f32 v[64:65], v[64:65], v[136:137]
	s_waitcnt vmcnt(7)
; __device__ __forceinline__ float bflo(unsigned w) { return __uint_as_float(w << 16); }
; __device__ __forceinline__ float bfhi(unsigned w) { return __uint_as_float(w & 0xffff0000u); }
; __device__ __forceinline__ unsigned pk2(float lo, float hi) { unsigned r; asm("v_cvt_pk_bf16_f32 %0, %1, %2" : "=v"(r) : "v"(lo), "v"(hi)); return r; }
; __device__ __forceinline__ float siluf_(float x) { return x * __builtin_amdgcn_rcpf(1.0f + __expf(-x)); }
;     __device__ __forceinline__ void operator()(const f32x4 (&acc)[2][2][4][2], const Unit& u, int wr, int wc, int fr, int fq) const {
;     ...
;             for (int ai = 0; ai < 2; ++ai)
; #pragma unroll
;                 for (int m = 0; m < 4; ++m) { const int row = row0 + ai * HALF + m * 16;
;                     const u32x4 z = __builtin_nontemporal_load((const u32x4*)(proj + (size_t)row * NPROJ + C_ZP + col));
;                     f32x4 v0 = (acc[ai][bj][m][0] + b0) * s0, v1 = (acc[ai][bj][m][1] + b1) * s1;
;                     v0[0] *= siluf_(bflo(z.x)); v0[1] *= siluf_(bfhi(z.x)); v0[2] *= siluf_(bflo(z.y)); v0[3] *= siluf_(bfhi(z.y));
;                     v1[0] *= siluf_(bflo(z.z)); v1[1] *= siluf_(bfhi(z.z)); v1[2] *= siluf_(bflo(z.w)); v1[3] *= siluf_(bfhi(z.w));
;                     u32x4 w; w.x = pk2(v0[0], v0[1]); w.y = pk2(v0[2], v0[3]); w.z = pk2(v1[0], v1[1]); w.w = pk2(v1[2], v1[3]);
;                     *(u32x4*)(a2 + (size_t)row * 4096 + 2048 + col) = w; } }
	v_mov_b32_e32 v144, v206
	v_mov_b32_e32 v145, v207
	v_mov_b32_e32 v146, v208
	v_mov_b32_e32 v147, v209
	s_mov_b32 s60, 0x6a100
	s_mov_b32 s61, 0
	v_lshl_add_u64 v[206:207], v[254:255], 0, s[60:61]
	global_load_dwordx4 v[206:209], v[206:207], off nt
	v_lshlrev_b32_e32 v193, 16, v147
	v_and_b32_e32 v147, 0xffff0000, v147
	v_lshlrev_b32_e32 v127, 16, v144
	v_and_b32_e32 v144, 0xffff0000, v144
	v_lshlrev_b32_e32 v177, 16, v145
	v_and_b32_e32 v145, 0xffff0000, v145
	v_lshlrev_b32_e32 v191, 16, v146
	v_and_b32_e32 v146, 0xffff0000, v146
	v_mul_f32_e32 v203, 0xbfb8aa3b, v147
	v_mul_f32_e32 v196, 0xbfb8aa3b, v127
	v_mul_f32_e32 v197, 0xbfb8aa3b, v144
	v_mul_f32_e32 v198, 0xbfb8aa3b, v177
	v_mul_f32_e32 v199, 0xbfb8aa3b, v145
	v_mul_f32_e32 v200, 0xbfb8aa3b, v191
	v_mul_f32_e32 v201, 0xbfb8aa3b, v146
	v_mul_f32_e32 v202, 0xbfb8aa3b, v193
	v_exp_f32_e32 v203, v203
	v_exp_f32_e32 v196, v196
	v_exp_f32_e32 v197, v197
	v_exp_f32_e32 v198, v198
	v_exp_f32_e32 v199, v199
	v_exp_f32_e32 v200, v200
	v_exp_f32_e32 v201, v201
	v_exp_f32_e32 v202, v202
	v_add_f32_e32 v203, 1.0, v203
	v_add_f32_e32 v196, 1.0, v196
	v_add_f32_e32 v197, 1.0, v197
	v_add_f32_e32 v198, 1.0, v198
	v_add_f32_e32 v199, 1.0, v199
	v_add_f32_e32 v200, 1.0, v200
	v_add_f32_e32 v201, 1.0, v201
	v_add_f32_e32 v202, 1.0, v202
	v_rcp_f32_e32 v203, v203
	v_rcp_f32_e32 v196, v196
	v_rcp_f32_e32 v197, v197
	v_rcp_f32_e32 v198, v198
	v_rcp_f32_e32 v199, v199
	v_rcp_f32_e32 v200, v200
	v_rcp_f32_e32 v201, v201
	v_rcp_f32_e32 v202, v202
	v_mul_f32_e32 v147, v203, v147
	v_mul_f32_e32 v127, v196, v127
	v_mul_f32_e32 v144, v197, v144
	v_mul_f32_e32 v177, v198, v177
	v_mul_f32_e32 v145, v199, v145
	v_mul_f32_e32 v191, v200, v191
	v_mul_f32_e32 v146, v201, v146
	v_mul_f32_e32 v193, v202, v193
	v_mul_f32_e32 v115, v115, v147
	v_mul_f32_e32 v116, v116, v127
	v_mul_f32_e32 v117, v117, v144
	v_mul_f32_e32 v118, v118, v177
	v_mul_f32_e32 v119, v119, v145
	v_mul_f32_e32 v127, v112, v191
	v_mul_f32_e32 v144, v113, v146
	v_mul_f32_e32 v145, v114, v193
	v_cvt_pk_bf16_f32 v112, v116, v117
	v_cvt_pk_bf16_f32 v113, v118, v119
	v_cvt_pk_bf16_f32 v114, v127, v144
	v_cvt_pk_bf16_f32 v115, v145, v115
	global_store_dwordx4 v[194:195], v[112:115], off
	v_ashrrev_i32_e32 v127, 31, v126
	v_lshlrev_b64 v[114:115], 13, v[126:127]
	v_or_b32_e32 v144, 48, v176
	v_lshl_add_u64 v[114:115], s[6:7], 0, v[114:115]
	v_mad_i64_i32 v[112:113], s[2:3], v144, s49, v[178:179]
	v_lshl_add_u64 v[114:115], v[114:115], 0, s[10:11]
	v_lshl_add_u64 v[112:113], v[112:113], 0, s[8:9]
	v_lshl_add_u64 v[146:147], v[114:115], 0, v[174:175]
	v_lshl_add_u64 v[126:127], v[112:113], 0, v[174:175]
	s_waitcnt vmcnt(8)
	v_mov_b32_e32 v116, v210
	v_mov_b32_e32 v117, v211
	v_mov_b32_e32 v118, v212
	v_mov_b32_e32 v119, v213
	s_mov_b32 s60, 0xd4100
	s_mov_b32 s61, 0
	v_lshl_add_u64 v[210:211], v[254:255], 0, s[60:61]
	global_load_dwordx4 v[210:213], v[210:211], off nt
	v_lshlrev_b32_e32 v183, 16, v119
	v_and_b32_e32 v119, 0xffff0000, v119
	v_lshlrev_b32_e32 v145, 16, v116
	v_and_b32_e32 v116, 0xffff0000, v116
	v_lshlrev_b32_e32 v177, 16, v117
	v_and_b32_e32 v117, 0xffff0000, v117
	v_lshlrev_b32_e32 v182, 16, v118
	v_and_b32_e32 v118, 0xffff0000, v118
	v_mul_f32_e32 v199, 0xbfb8aa3b, v119
	v_mul_f32_e32 v191, 0xbfb8aa3b, v145
	v_mul_f32_e32 v193, 0xbfb8aa3b, v116
	v_mul_f32_e32 v194, 0xbfb8aa3b, v177
	v_mul_f32_e32 v195, 0xbfb8aa3b, v117
	v_mul_f32_e32 v196, 0xbfb8aa3b, v182
	v_mul_f32_e32 v197, 0xbfb8aa3b, v118
	v_mul_f32_e32 v198, 0xbfb8aa3b, v183
	v_exp_f32_e32 v199, v199
	v_exp_f32_e32 v191, v191
	v_exp_f32_e32 v193, v193
	v_exp_f32_e32 v194, v194
	v_exp_f32_e32 v195, v195
	v_exp_f32_e32 v196, v196
	v_exp_f32_e32 v197, v197
	v_exp_f32_e32 v198, v198
	v_add_f32_e32 v199, 1.0, v199
	v_add_f32_e32 v191, 1.0, v191
	v_add_f32_e32 v193, 1.0, v193
	v_add_f32_e32 v194, 1.0, v194
	v_add_f32_e32 v195, 1.0, v195
	v_add_f32_e32 v196, 1.0, v196
	v_add_f32_e32 v197, 1.0, v197
	v_add_f32_e32 v198, 1.0, v198
	v_rcp_f32_e32 v199, v199
	v_rcp_f32_e32 v191, v191
	v_rcp_f32_e32 v193, v193
	v_rcp_f32_e32 v194, v194
	v_rcp_f32_e32 v195, v195
	v_rcp_f32_e32 v196, v196
	v_rcp_f32_e32 v197, v197
	v_rcp_f32_e32 v198, v198
	v_mul_f32_e32 v119, v199, v119
	v_mul_f32_e32 v145, v191, v145
	v_mul_f32_e32 v116, v193, v116
	v_mul_f32_e32 v177, v194, v177
	v_mul_f32_e32 v117, v195, v117
	v_mul_f32_e32 v182, v196, v182
	v_mul_f32_e32 v118, v197, v118
	v_mul_f32_e32 v183, v198, v183
	v_mul_f32_e32 v107, v107, v119
	v_mul_f32_e32 v108, v108, v145
	v_mul_f32_e32 v109, v109, v116
	v_mul_f32_e32 v110, v110, v177
	v_mul_f32_e32 v111, v111, v117
	v_mul_f32_e32 v116, v104, v182
	v_mul_f32_e32 v117, v105, v118
	v_mul_f32_e32 v118, v106, v183
	v_cvt_pk_bf16_f32 v104, v108, v109
	v_cvt_pk_bf16_f32 v105, v110, v111
	v_cvt_pk_bf16_f32 v106, v116, v117
	v_cvt_pk_bf16_f32 v107, v118, v107
	global_store_dwordx4 v[146:147], v[104:107], off
	v_ashrrev_i32_e32 v145, 31, v144
	v_lshlrev_b64 v[106:107], 13, v[144:145]
	v_add_u32_e32 v116, 0x80, v176
	v_lshl_add_u64 v[106:107], s[6:7], 0, v[106:107]
	v_mad_i64_i32 v[104:105], s[2:3], v116, s49, v[178:179]
	v_lshl_add_u64 v[106:107], v[106:107], 0, s[10:11]
	v_lshl_add_u64 v[104:105], v[104:105], 0, s[8:9]
	v_lshl_add_u64 v[126:127], v[106:107], 0, v[174:175]
	v_lshl_add_u64 v[118:119], v[104:105], 0, v[174:175]
	s_waitcnt vmcnt(9)
; __device__ __forceinline__ float bflo(unsigned w) { return __uint_as_float(w << 16); }
; __device__ __forceinline__ float bfhi(unsigned w) { return __uint_as_float(w & 0xffff0000u); }
; __device__ __forceinline__ unsigned pk2(float lo, float hi) { unsigned r; asm("v_cvt_pk_bf16_f32 %0, %1, %2" : "=v"(r) : "v"(lo), "v"(hi)); return r; }
; __device__ __forceinline__ float siluf_(float x) { return x * __builtin_amdgcn_rcpf(1.0f + __expf(-x)); }
;     __device__ __forceinline__ void operator()(const f32x4 (&acc)[2][2][4][2], const Unit& u, int wr, int wc, int fr, int fq) const {
;     ...
;             for (int ai = 0; ai < 2; ++ai)
; #pragma unroll
;                 for (int m = 0; m < 4; ++m) { const int row = row0 + ai * HALF + m * 16;
;                     const u32x4 z = __builtin_nontemporal_load((const u32x4*)(proj + (size_t)row * NPROJ + C_ZP + col));
;                     f32x4 v0 = (acc[ai][bj][m][0] + b0) * s0, v1 = (acc[ai][bj][m][1] + b1) * s1;
;                     v0[0] *= siluf_(bflo(z.x)); v0[1] *= siluf_(bfhi(z.x)); v0[2] *= siluf_(bflo(z.y)); v0[3] *= siluf_(bfhi(z.y));
;                     v1[0] *= siluf_(bflo(z.z)); v1[1] *= siluf_(bfhi(z.z)); v1[2] *= siluf_(bflo(z.w)); v1[3] *= siluf_(bfhi(z.w));
;                     u32x4 w; w.x = pk2(v0[0], v0[1]); w.y = pk2(v0[2], v0[3]); w.z = pk2(v1[0], v1[1]); w.w = pk2(v1[2], v1[3]);
;                     *(u32x4*)(a2 + (size_t)row * 4096 + 2048 + col) = w; } }
	v_mov_b32_e32 v108, v214
	v_mov_b32_e32 v109, v215
	v_mov_b32_e32 v110, v216
	v_mov_b32_e32 v111, v217
	s_mov_b32 s60, 0x13e100
	s_mov_b32 s61, 0
	v_lshl_add_u64 v[214:215], v[254:255], 0, s[60:61]
	global_load_dwordx4 v[214:217], v[214:215], off nt
	v_lshlrev_b32_e32 v146, 16, v111
	v_and_b32_e32 v111, 0xffff0000, v111
	v_lshlrev_b32_e32 v117, 16, v108
	v_and_b32_e32 v108, 0xffff0000, v108
	v_lshlrev_b32_e32 v144, 16, v109
	v_and_b32_e32 v109, 0xffff0000, v109
	v_lshlrev_b32_e32 v145, 16, v110
	v_and_b32_e32 v110, 0xffff0000, v110
	v_mul_f32_e32 v195, 0xbfb8aa3b, v111
	v_mul_f32_e32 v147, 0xbfb8aa3b, v117
	v_mul_f32_e32 v177, 0xbfb8aa3b, v108
	v_mul_f32_e32 v182, 0xbfb8aa3b, v144
	v_mul_f32_e32 v183, 0xbfb8aa3b, v109
	v_mul_f32_e32 v191, 0xbfb8aa3b, v145
	v_mul_f32_e32 v193, 0xbfb8aa3b, v110
	v_mul_f32_e32 v194, 0xbfb8aa3b, v146
	v_exp_f32_e32 v195, v195
	v_exp_f32_e32 v147, v147
	v_exp_f32_e32 v177, v177
	v_exp_f32_e32 v182, v182
	v_exp_f32_e32 v183, v183
	v_exp_f32_e32 v191, v191
	v_exp_f32_e32 v193, v193
	v_exp_f32_e32 v194, v194
	v_add_f32_e32 v195, 1.0, v195
	v_add_f32_e32 v147, 1.0, v147
	v_add_f32_e32 v177, 1.0, v177
	v_add_f32_e32 v182, 1.0, v182
	v_add_f32_e32 v183, 1.0, v183
	v_add_f32_e32 v191, 1.0, v191
	v_add_f32_e32 v193, 1.0, v193
	v_add_f32_e32 v194, 1.0, v194
	v_rcp_f32_e32 v195, v195
	v_rcp_f32_e32 v147, v147
	v_rcp_f32_e32 v177, v177
	v_rcp_f32_e32 v182, v182
	v_rcp_f32_e32 v183, v183
	v_rcp_f32_e32 v191, v191
	v_rcp_f32_e32 v193, v193
	v_rcp_f32_e32 v194, v194
	v_mul_f32_e32 v111, v195, v111
	v_mul_f32_e32 v117, v147, v117
	v_mul_f32_e32 v108, v177, v108
	v_mul_f32_e32 v144, v182, v144
	v_mul_f32_e32 v109, v183, v109
	v_mul_f32_e32 v145, v191, v145
	v_mul_f32_e32 v110, v193, v110
	v_mul_f32_e32 v146, v194, v146
	v_mul_f32_e32 v99, v99, v111
	v_mul_f32_e32 v100, v100, v117
	v_mul_f32_e32 v101, v101, v108
	v_mul_f32_e32 v102, v102, v144
	v_mul_f32_e32 v103, v103, v109
	v_mul_f32_e32 v108, v96, v145
	v_mul_f32_e32 v109, v97, v110
	v_mul_f32_e32 v110, v98, v146
	v_cvt_pk_bf16_f32 v96, v100, v101
	v_cvt_pk_bf16_f32 v97, v102, v103
	v_cvt_pk_bf16_f32 v98, v108, v109
	v_cvt_pk_bf16_f32 v99, v110, v99
	global_store_dwordx4 v[126:127], v[96:99], off
	v_ashrrev_i32_e32 v117, 31, v116
	v_lshlrev_b64 v[98:99], 13, v[116:117]
	v_add_u32_e32 v108, 0x90, v176
	v_lshl_add_u64 v[98:99], s[6:7], 0, v[98:99]
	v_mad_i64_i32 v[96:97], s[2:3], v108, s49, v[178:179]
	v_lshl_add_u64 v[98:99], v[98:99], 0, s[10:11]
	v_lshl_add_u64 v[96:97], v[96:97], 0, s[8:9]
	v_lshl_add_u64 v[116:117], v[98:99], 0, v[174:175]
	v_lshl_add_u64 v[110:111], v[96:97], 0, v[174:175]
	s_waitcnt vmcnt(10)
	v_mov_b32_e32 v100, v218
	v_mov_b32_e32 v101, v219
	v_mov_b32_e32 v102, v220
	v_mov_b32_e32 v103, v221
	s_mov_b32 s60, 0x350100
	s_mov_b32 s61, 0
	v_lshl_add_u64 v[218:219], v[254:255], 0, s[60:61]
	global_load_dwordx4 v[218:221], v[218:219], off nt
	v_lshlrev_b32_e32 v126, 16, v103
	v_and_b32_e32 v103, 0xffff0000, v103
	v_lshlrev_b32_e32 v109, 16, v100
	v_and_b32_e32 v100, 0xffff0000, v100
	v_lshlrev_b32_e32 v118, 16, v101
	v_and_b32_e32 v101, 0xffff0000, v101
	v_lshlrev_b32_e32 v119, 16, v102
	v_and_b32_e32 v102, 0xffff0000, v102
	v_mul_f32_e32 v183, 0xbfb8aa3b, v103
	v_mul_f32_e32 v127, 0xbfb8aa3b, v109
	v_mul_f32_e32 v144, 0xbfb8aa3b, v100
	v_mul_f32_e32 v145, 0xbfb8aa3b, v118
	v_mul_f32_e32 v146, 0xbfb8aa3b, v101
	v_mul_f32_e32 v147, 0xbfb8aa3b, v119
	v_mul_f32_e32 v177, 0xbfb8aa3b, v102
	v_mul_f32_e32 v182, 0xbfb8aa3b, v126
	v_exp_f32_e32 v183, v183
	v_exp_f32_e32 v127, v127
	v_exp_f32_e32 v144, v144
	v_exp_f32_e32 v145, v145
	v_exp_f32_e32 v146, v146
	v_exp_f32_e32 v147, v147
	v_exp_f32_e32 v177, v177
	v_exp_f32_e32 v182, v182
	v_add_f32_e32 v183, 1.0, v183
	v_add_f32_e32 v127, 1.0, v127
	v_add_f32_e32 v144, 1.0, v144
	v_add_f32_e32 v145, 1.0, v145
	v_add_f32_e32 v146, 1.0, v146
	v_add_f32_e32 v147, 1.0, v147
	v_add_f32_e32 v177, 1.0, v177
	v_add_f32_e32 v182, 1.0, v182
	v_rcp_f32_e32 v183, v183
	v_rcp_f32_e32 v127, v127
	v_rcp_f32_e32 v144, v144
	v_rcp_f32_e32 v145, v145
	v_rcp_f32_e32 v146, v146
	v_rcp_f32_e32 v147, v147
	v_rcp_f32_e32 v177, v177
	v_rcp_f32_e32 v182, v182
	v_mul_f32_e32 v103, v183, v103
	v_mul_f32_e32 v109, v127, v109
	v_mul_f32_e32 v100, v144, v100
	v_mul_f32_e32 v118, v145, v118
	v_mul_f32_e32 v101, v146, v101
	v_mul_f32_e32 v119, v147, v119
	v_mul_f32_e32 v102, v177, v102
	v_mul_f32_e32 v126, v182, v126
	v_mul_f32_e32 v91, v91, v103
	v_mul_f32_e32 v92, v92, v109
	v_mul_f32_e32 v93, v93, v100
	v_mul_f32_e32 v94, v94, v118
	v_mul_f32_e32 v95, v95, v101
	v_mul_f32_e32 v100, v88, v119
	v_mul_f32_e32 v101, v89, v102
	v_mul_f32_e32 v102, v90, v126
	v_cvt_pk_bf16_f32 v88, v92, v93
	v_cvt_pk_bf16_f32 v89, v94, v95
	v_cvt_pk_bf16_f32 v90, v100, v101
	v_cvt_pk_bf16_f32 v91, v102, v91
	global_store_dwordx4 v[116:117], v[88:91], off
	v_ashrrev_i32_e32 v109, 31, v108
	v_lshlrev_b64 v[90:91], 13, v[108:109]
	v_add_u32_e32 v100, 0xa0, v176
	v_lshl_add_u64 v[90:91], s[6:7], 0, v[90:91]
	v_mad_i64_i32 v[88:89], s[2:3], v100, s49, v[178:179]
	v_lshl_add_u64 v[90:91], v[90:91], 0, s[10:11]
	v_lshl_add_u64 v[88:89], v[88:89], 0, s[8:9]
	v_lshl_add_u64 v[108:109], v[90:91], 0, v[174:175]
	v_lshl_add_u64 v[102:103], v[88:89], 0, v[174:175]
	s_waitcnt vmcnt(11)
; __device__ __forceinline__ float bflo(unsigned w) { return __uint_as_float(w << 16); }
; __device__ __forceinline__ float bfhi(unsigned w) { return __uint_as_float(w & 0xffff0000u); }
; __device__ __forceinline__ unsigned pk2(float lo, float hi) { unsigned r; asm("v_cvt_pk_bf16_f32 %0, %1, %2" : "=v"(r) : "v"(lo), "v"(hi)); return r; }
; __device__ __forceinline__ float siluf_(float x) { return x * __builtin_amdgcn_rcpf(1.0f + __expf(-x)); }
;     __device__ __forceinline__ void operator()(const f32x4 (&acc)[2][2][4][2], const Unit& u, int wr, int wc, int fr, int fq) const {
;     ...
;             for (int ai = 0; ai < 2; ++ai)
; #pragma unroll
;                 for (int m = 0; m < 4; ++m) { const int row = row0 + ai * HALF + m * 16;
;                     const u32x4 z = __builtin_nontemporal_load((const u32x4*)(proj + (size_t)row * NPROJ + C_ZP + col));
;                     f32x4 v0 = (acc[ai][bj][m][0] + b0) * s0, v1 = (acc[ai][bj][m][1] + b1) * s1;
;                     v0[0] *= siluf_(bflo(z.x)); v0[1] *= siluf_(bfhi(z.x)); v0[2] *= siluf_(bflo(z.y)); v0[3] *= siluf_(bfhi(z.y));
;                     v1[0] *= siluf_(bflo(z.z)); v1[1] *= siluf_(bfhi(z.z)); v1[2] *= siluf_(bflo(z.w)); v1[3] *= siluf_(bfhi(z.w));
;                     u32x4 w; w.x = pk2(v0[0], v0[1]); w.y = pk2(v0[2], v0[3]); w.z = pk2(v1[0], v1[1]); w.w = pk2(v1[2], v1[3]);
;                     *(u32x4*)(a2 + (size_t)row * 4096 + 2048 + col) = w; } }
	v_mov_b32_e32 v92, v222
	v_mov_b32_e32 v93, v223
	v_mov_b32_e32 v94, v224
	v_mov_b32_e32 v95, v225
	s_mov_b32 s60, 0x3ba100
	s_mov_b32 s61, 0
	v_lshl_add_u64 v[222:223], v[254:255], 0, s[60:61]
	global_load_dwordx4 v[222:225], v[222:223], off nt
	v_lshlrev_b32_e32 v116, 16, v95
	v_and_b32_e32 v95, 0xffff0000, v95
	v_lshlrev_b32_e32 v101, 16, v92
	v_and_b32_e32 v92, 0xffff0000, v92
	v_lshlrev_b32_e32 v110, 16, v93
	v_and_b32_e32 v93, 0xffff0000, v93
	v_lshlrev_b32_e32 v111, 16, v94
	v_and_b32_e32 v94, 0xffff0000, v94
	v_mul_f32_e32 v146, 0xbfb8aa3b, v95
	v_mul_f32_e32 v117, 0xbfb8aa3b, v101
	v_mul_f32_e32 v118, 0xbfb8aa3b, v92
	v_mul_f32_e32 v119, 0xbfb8aa3b, v110
	v_mul_f32_e32 v126, 0xbfb8aa3b, v93
	v_mul_f32_e32 v127, 0xbfb8aa3b, v111
	v_mul_f32_e32 v144, 0xbfb8aa3b, v94
	v_mul_f32_e32 v145, 0xbfb8aa3b, v116
	v_exp_f32_e32 v146, v146
	v_exp_f32_e32 v117, v117
	v_exp_f32_e32 v118, v118
	v_exp_f32_e32 v119, v119
	v_exp_f32_e32 v126, v126
	v_exp_f32_e32 v127, v127
	v_exp_f32_e32 v144, v144
	v_exp_f32_e32 v145, v145
	v_add_f32_e32 v146, 1.0, v146
	v_add_f32_e32 v117, 1.0, v117
	v_add_f32_e32 v118, 1.0, v118
	v_add_f32_e32 v119, 1.0, v119
	v_add_f32_e32 v126, 1.0, v126
	v_add_f32_e32 v127, 1.0, v127
	v_add_f32_e32 v144, 1.0, v144
	v_add_f32_e32 v145, 1.0, v145
	v_rcp_f32_e32 v146, v146
	v_rcp_f32_e32 v117, v117
	v_rcp_f32_e32 v118, v118
	v_rcp_f32_e32 v119, v119
	v_rcp_f32_e32 v126, v126
	v_rcp_f32_e32 v127, v127
	v_rcp_f32_e32 v144, v144
	v_rcp_f32_e32 v145, v145
	v_mul_f32_e32 v95, v146, v95
	v_mul_f32_e32 v101, v117, v101
	v_mul_f32_e32 v92, v118, v92
	v_mul_f32_e32 v110, v119, v110
	v_mul_f32_e32 v93, v126, v93
	v_mul_f32_e32 v111, v127, v111
	v_mul_f32_e32 v94, v144, v94
	v_mul_f32_e32 v116, v145, v116
	v_mul_f32_e32 v83, v83, v95
	v_mul_f32_e32 v84, v84, v101
	v_mul_f32_e32 v85, v85, v92
	v_mul_f32_e32 v86, v86, v110
	v_mul_f32_e32 v87, v87, v93
	v_mul_f32_e32 v92, v80, v111
	v_mul_f32_e32 v93, v81, v94
	v_mul_f32_e32 v94, v82, v116
	v_cvt_pk_bf16_f32 v80, v84, v85
	v_cvt_pk_bf16_f32 v81, v86, v87
	v_cvt_pk_bf16_f32 v82, v92, v93
	v_cvt_pk_bf16_f32 v83, v94, v83
	global_store_dwordx4 v[108:109], v[80:83], off
	v_ashrrev_i32_e32 v101, 31, v100
	v_lshlrev_b64 v[84:85], 13, v[100:101]
	v_add_u32_e32 v80, 0xb0, v176
	v_lshl_add_u64 v[84:85], s[6:7], 0, v[84:85]
	v_mad_i64_i32 v[82:83], s[2:3], v80, s49, v[178:179]
	v_lshl_add_u64 v[84:85], v[84:85], 0, s[10:11]
	v_lshl_add_u64 v[82:83], v[82:83], 0, s[8:9]
	v_lshl_add_u64 v[100:101], v[84:85], 0, v[174:175]
	v_lshl_add_u64 v[86:87], v[82:83], 0, v[174:175]
	s_waitcnt vmcnt(12)
	v_mov_b32_e32 v92, v226
	v_mov_b32_e32 v93, v227
	v_mov_b32_e32 v94, v228
	v_mov_b32_e32 v95, v229
	s_mov_b32 s60, 0x424100
	s_mov_b32 s61, 0
	v_lshl_add_u64 v[226:227], v[254:255], 0, s[60:61]
	global_load_dwordx4 v[226:229], v[226:227], off nt
	v_lshlrev_b32_e32 v108, 16, v95
	v_and_b32_e32 v95, 0xffff0000, v95
	v_lshlrev_b32_e32 v81, 16, v92
	v_and_b32_e32 v92, 0xffff0000, v92
	v_lshlrev_b32_e32 v102, 16, v93
	v_and_b32_e32 v93, 0xffff0000, v93
	v_lshlrev_b32_e32 v103, 16, v94
	v_and_b32_e32 v94, 0xffff0000, v94
	v_mul_f32_e32 v126, 0xbfb8aa3b, v95
	v_mul_f32_e32 v109, 0xbfb8aa3b, v81
	v_mul_f32_e32 v110, 0xbfb8aa3b, v92
	v_mul_f32_e32 v111, 0xbfb8aa3b, v102
	v_mul_f32_e32 v116, 0xbfb8aa3b, v93
	v_mul_f32_e32 v117, 0xbfb8aa3b, v103
	v_mul_f32_e32 v118, 0xbfb8aa3b, v94
	v_mul_f32_e32 v119, 0xbfb8aa3b, v108
	v_exp_f32_e32 v126, v126
	v_exp_f32_e32 v109, v109
	v_exp_f32_e32 v110, v110
	v_exp_f32_e32 v111, v111
	v_exp_f32_e32 v116, v116
	v_exp_f32_e32 v117, v117
	v_exp_f32_e32 v118, v118
	v_exp_f32_e32 v119, v119
	v_add_f32_e32 v126, 1.0, v126
	v_add_f32_e32 v109, 1.0, v109
	v_add_f32_e32 v110, 1.0, v110
	v_add_f32_e32 v111, 1.0, v111
	v_add_f32_e32 v116, 1.0, v116
	v_add_f32_e32 v117, 1.0, v117
	v_add_f32_e32 v118, 1.0, v118
	v_add_f32_e32 v119, 1.0, v119
	v_rcp_f32_e32 v126, v126
	v_rcp_f32_e32 v109, v109
	v_rcp_f32_e32 v110, v110
	v_rcp_f32_e32 v111, v111
	v_rcp_f32_e32 v116, v116
	v_rcp_f32_e32 v117, v117
	v_rcp_f32_e32 v118, v118
	v_rcp_f32_e32 v119, v119
	v_mul_f32_e32 v95, v126, v95
	v_mul_f32_e32 v81, v109, v81
	v_mul_f32_e32 v92, v110, v92
	v_mul_f32_e32 v102, v111, v102
	v_mul_f32_e32 v93, v116, v93
	v_mul_f32_e32 v103, v117, v103
	v_mul_f32_e32 v94, v118, v94
	v_mul_f32_e32 v108, v119, v108
	v_mul_f32_e32 v75, v75, v95
	v_mul_f32_e32 v76, v76, v81
	v_mul_f32_e32 v77, v77, v92
	v_mul_f32_e32 v78, v78, v102
	v_mul_f32_e32 v79, v79, v93
	v_mul_f32_e32 v81, v72, v103
	v_mul_f32_e32 v92, v73, v94
	v_mul_f32_e32 v93, v74, v108
	v_cvt_pk_bf16_f32 v72, v76, v77
	v_cvt_pk_bf16_f32 v73, v78, v79
	v_cvt_pk_bf16_f32 v74, v81, v92
	v_cvt_pk_bf16_f32 v75, v93, v75
	global_store_dwordx4 v[100:101], v[72:75], off
	v_ashrrev_i32_e32 v81, 31, v80
	v_lshlrev_b64 v[76:77], 13, v[80:81]
	v_lshl_add_u64 v[76:77], s[6:7], 0, v[76:77]
	v_lshl_add_u64 v[80:81], v[76:77], 0, s[10:11]
	v_lshl_add_u64 v[76:77], v[80:81], 0, v[174:175]
	v_and_b32_e32 v109, 0xffff0000, v151
	v_lshlrev_b32_e32 v108, 16, v151
	s_waitcnt vmcnt(13)
; __device__ __forceinline__ float bflo(unsigned w) { return __uint_as_float(w << 16); }
; __device__ __forceinline__ float bfhi(unsigned w) { return __uint_as_float(w & 0xffff0000u); }
; __device__ __forceinline__ unsigned pk2(float lo, float hi) { unsigned r; asm("v_cvt_pk_bf16_f32 %0, %1, %2" : "=v"(r) : "v"(lo), "v"(hi)); return r; }
; __device__ __forceinline__ float siluf_(float x) { return x * __builtin_amdgcn_rcpf(1.0f + __expf(-x)); }
;     __device__ __forceinline__ void operator()(const f32x4 (&acc)[2][2][4][2], const Unit& u, int wr, int wc, int fr, int fq) const {
;     ...
;         for (int bj = 0; bj < 2; ++bj) { const int col = col0 + bj * HALF;
;             const f32x4 b0 = *(const f32x4*)(bias + col), b1 = *(const f32x4*)(bias + col + 4), s0 = *(const f32x4*)(scale + col), s1 = *(const f32x4*)(scale + col + 4);
; #pragma unroll
;             for (int ai = 0; ai < 2; ++ai)
; #pragma unroll
;                 for (int m = 0; m < 4; ++m) { const int row = row0 + ai * HALF + m * 16;
;                     const u32x4 z = __builtin_nontemporal_load((const u32x4*)(proj + (size_t)row * NPROJ + C_ZP + col));
;                     f32x4 v0 = (acc[ai][bj][m][0] + b0) * s0, v1 = (acc[ai][bj][m][1] + b1) * s1;
;                     v0[0] *= siluf_(bflo(z.x)); v0[1] *= siluf_(bfhi(z.x)); v0[2] *= siluf_(bflo(z.y)); v0[3] *= siluf_(bfhi(z.y));
;                     v1[0] *= siluf_(bflo(z.z)); v1[1] *= siluf_(bfhi(z.z)); v1[2] *= siluf_(bflo(z.w)); v1[3] *= siluf_(bfhi(z.w));
;                     u32x4 w; w.x = pk2(v0[0], v0[1]); w.y = pk2(v0[2], v0[3]); w.z = pk2(v1[0], v1[1]); w.w = pk2(v1[2], v1[3]);
;                     *(u32x4*)(a2 + (size_t)row * 4096 + 2048 + col) = w; } }
	v_mov_b32_e32 v72, v230
	v_mov_b32_e32 v73, v231
	v_mov_b32_e32 v74, v232
	v_mov_b32_e32 v75, v233
	s_mov_b32 s60, 0x48e100
	s_mov_b32 s61, 0
	v_lshl_add_u64 v[230:231], v[254:255], 0, s[60:61]
	global_load_dwordx4 v[230:233], v[230:231], off nt
	v_lshlrev_b32_e32 v87, 16, v75
	v_and_b32_e32 v75, 0xffff0000, v75
	v_lshlrev_b32_e32 v78, 16, v72
	v_and_b32_e32 v72, 0xffff0000, v72
	v_lshlrev_b32_e32 v79, 16, v73
	v_and_b32_e32 v73, 0xffff0000, v73
	v_lshlrev_b32_e32 v86, 16, v74
	v_and_b32_e32 v74, 0xffff0000, v74
	v_mul_f32_e32 v103, 0xbfb8aa3b, v75
	v_mul_f32_e32 v92, 0xbfb8aa3b, v78
	v_mul_f32_e32 v93, 0xbfb8aa3b, v72
	v_mul_f32_e32 v94, 0xbfb8aa3b, v79
	v_mul_f32_e32 v95, 0xbfb8aa3b, v73
	v_mul_f32_e32 v100, 0xbfb8aa3b, v86
	v_mul_f32_e32 v101, 0xbfb8aa3b, v74
	v_mul_f32_e32 v102, 0xbfb8aa3b, v87
	v_exp_f32_e32 v103, v103
	v_exp_f32_e32 v92, v92
	v_exp_f32_e32 v93, v93
	v_exp_f32_e32 v94, v94
	v_exp_f32_e32 v95, v95
	v_exp_f32_e32 v100, v100
	v_exp_f32_e32 v101, v101
	v_exp_f32_e32 v102, v102
	v_add_f32_e32 v103, 1.0, v103
	v_add_f32_e32 v92, 1.0, v92
	v_add_f32_e32 v93, 1.0, v93
	v_add_f32_e32 v94, 1.0, v94
	v_add_f32_e32 v95, 1.0, v95
	v_add_f32_e32 v100, 1.0, v100
	v_add_f32_e32 v101, 1.0, v101
	v_add_f32_e32 v102, 1.0, v102
	v_rcp_f32_e32 v103, v103
	v_rcp_f32_e32 v92, v92
	v_rcp_f32_e32 v93, v93
	v_rcp_f32_e32 v94, v94
	v_rcp_f32_e32 v95, v95
	v_rcp_f32_e32 v100, v100
	v_rcp_f32_e32 v101, v101
	v_rcp_f32_e32 v102, v102
	v_mul_f32_e32 v75, v103, v75
	v_mul_f32_e32 v78, v92, v78
	v_mul_f32_e32 v72, v93, v72
	v_mul_f32_e32 v79, v94, v79
	v_mul_f32_e32 v73, v95, v73
	v_mul_f32_e32 v86, v100, v86
	v_mul_f32_e32 v74, v101, v74
	v_mul_f32_e32 v87, v102, v87
	v_mul_f32_e32 v67, v67, v75
	v_mul_f32_e32 v68, v68, v78
	v_mul_f32_e32 v69, v69, v72
	v_mul_f32_e32 v70, v70, v79
	v_mul_f32_e32 v71, v71, v73
	v_mul_f32_e32 v72, v64, v86
	v_mul_f32_e32 v73, v65, v74
	v_mul_f32_e32 v74, v66, v87
	v_cvt_pk_bf16_f32 v64, v68, v69
	v_cvt_pk_bf16_f32 v65, v70, v71
	v_cvt_pk_bf16_f32 v66, v72, v73
	v_cvt_pk_bf16_f32 v67, v74, v67
	global_store_dwordx4 v[76:77], v[64:67], off
	global_load_dwordx4 v[76:79], v[170:171], off offset:512
	s_nop 0
	global_load_dwordx4 v[72:75], v[170:171], off offset:528
	global_load_dwordx4 v[68:71], v[172:173], off offset:512
	global_load_dwordx4 v[64:67], v[172:173], off offset:528
	v_lshl_add_u64 v[86:87], v[124:125], 0, v[168:169]
	v_lshlrev_b32_e32 v94, 16, v148
	v_and_b32_e32 v95, 0xffff0000, v148
	v_lshlrev_b32_e32 v100, 16, v149
	v_and_b32_e32 v101, 0xffff0000, v149
	v_lshlrev_b32_e32 v102, 16, v150
	v_and_b32_e32 v103, 0xffff0000, v150
	v_mul_f32_e32 v125, 0xbfb8aa3b, v109
	v_mul_f32_e32 v110, 0xbfb8aa3b, v94
	v_mul_f32_e32 v111, 0xbfb8aa3b, v95
	v_mul_f32_e32 v116, 0xbfb8aa3b, v100
	v_mul_f32_e32 v117, 0xbfb8aa3b, v101
	v_mul_f32_e32 v118, 0xbfb8aa3b, v102
	v_mul_f32_e32 v119, 0xbfb8aa3b, v103
	v_mul_f32_e32 v124, 0xbfb8aa3b, v108
	v_exp_f32_e32 v125, v125
	v_exp_f32_e32 v110, v110
	v_exp_f32_e32 v111, v111
	v_exp_f32_e32 v116, v116
	v_exp_f32_e32 v117, v117
	v_exp_f32_e32 v118, v118
	v_exp_f32_e32 v119, v119
	v_exp_f32_e32 v124, v124
	v_add_f32_e32 v125, 1.0, v125
	v_add_f32_e32 v110, 1.0, v110
	v_add_f32_e32 v111, 1.0, v111
	v_add_f32_e32 v116, 1.0, v116
	v_add_f32_e32 v117, 1.0, v117
	v_add_f32_e32 v118, 1.0, v118
	v_add_f32_e32 v119, 1.0, v119
	v_add_f32_e32 v124, 1.0, v124
	v_rcp_f32_e32 v125, v125
	v_rcp_f32_e32 v110, v110
	v_rcp_f32_e32 v111, v111
	v_rcp_f32_e32 v116, v116
	v_rcp_f32_e32 v117, v117
	v_rcp_f32_e32 v118, v118
	v_rcp_f32_e32 v119, v119
	v_rcp_f32_e32 v124, v124
	v_mul_f32_e32 v109, v125, v109
	v_lshl_add_u64 v[92:93], v[180:181], 0, v[168:169]
	v_mul_f32_e32 v94, v110, v94
	v_mul_f32_e32 v95, v111, v95
	v_mul_f32_e32 v100, v116, v100
	v_mul_f32_e32 v101, v117, v101
	v_mul_f32_e32 v102, v118, v102
	v_mul_f32_e32 v103, v119, v103
	v_mul_f32_e32 v108, v124, v108
	s_waitcnt vmcnt(0)
	v_pk_add_f32 v[62:63], v[62:63], v[78:79]
	v_pk_add_f32 v[58:59], v[58:59], v[74:75]
	v_pk_add_f32 v[60:61], v[60:61], v[76:77]
	v_pk_add_f32 v[56:57], v[56:57], v[72:73]
	v_pk_mul_f32 v[58:59], v[58:59], v[66:67]
	v_pk_mul_f32 v[62:63], v[62:63], v[70:71]
	v_pk_mul_f32 v[60:61], v[60:61], v[68:69]
	v_pk_mul_f32 v[56:57], v[56:57], v[64:65]
	v_mul_f32_e32 v59, v59, v109
	v_mul_f32_e32 v60, v60, v94
	v_mul_f32_e32 v61, v61, v95
	v_mul_f32_e32 v62, v62, v100
	v_mul_f32_e32 v63, v63, v101
	v_mul_f32_e32 v94, v56, v102
	v_mul_f32_e32 v95, v57, v103
	v_mul_f32_e32 v100, v58, v108
	v_cvt_pk_bf16_f32 v56, v60, v61
	v_cvt_pk_bf16_f32 v57, v62, v63
	v_cvt_pk_bf16_f32 v58, v94, v95
	v_cvt_pk_bf16_f32 v59, v100, v59
	global_store_dwordx4 v[92:93], v[56:59], off
	v_pk_add_f32 v[50:51], v[50:51], v[74:75]
	v_pk_add_f32 v[54:55], v[54:55], v[78:79]
	v_pk_add_f32 v[52:53], v[52:53], v[76:77]
	v_pk_add_f32 v[48:49], v[48:49], v[72:73]
	v_pk_mul_f32 v[50:51], v[50:51], v[66:67]
	v_lshl_add_u64 v[62:63], v[122:123], 0, v[168:169]
	v_pk_mul_f32 v[54:55], v[54:55], v[70:71]
	v_pk_mul_f32 v[52:53], v[52:53], v[68:69]
	v_pk_mul_f32 v[48:49], v[48:49], v[64:65]
	v_lshl_add_u64 v[60:61], v[120:121], 0, v[168:169]
	v_pk_add_f32 v[42:43], v[42:43], v[74:75]
	v_pk_add_f32 v[46:47], v[46:47], v[78:79]
	v_pk_add_f32 v[44:45], v[44:45], v[76:77]
	v_pk_add_f32 v[40:41], v[40:41], v[72:73]
	v_pk_mul_f32 v[42:43], v[42:43], v[66:67]
	v_pk_mul_f32 v[46:47], v[46:47], v[70:71]
	v_pk_mul_f32 v[44:45], v[44:45], v[68:69]
	v_pk_mul_f32 v[40:41], v[40:41], v[64:65]
	v_pk_add_f32 v[34:35], v[34:35], v[74:75]
	v_pk_add_f32 v[38:39], v[38:39], v[78:79]
	v_pk_add_f32 v[36:37], v[36:37], v[76:77]
	v_pk_add_f32 v[32:33], v[32:33], v[72:73]
; __device__ __forceinline__ float bflo(unsigned w) { return __uint_as_float(w << 16); }
; __device__ __forceinline__ float bfhi(unsigned w) { return __uint_as_float(w & 0xffff0000u); }
; __device__ __forceinline__ unsigned pk2(float lo, float hi) { unsigned r; asm("v_cvt_pk_bf16_f32 %0, %1, %2" : "=v"(r) : "v"(lo), "v"(hi)); return r; }
; __device__ __forceinline__ float siluf_(float x) { return x * __builtin_amdgcn_rcpf(1.0f + __expf(-x)); }
;     __device__ __forceinline__ void operator()(const f32x4 (&acc)[2][2][4][2], const Unit& u, int wr, int wc, int fr, int fq) const {
;     ...
;             for (int ai = 0; ai < 2; ++ai)
; #pragma unroll
;                 for (int m = 0; m < 4; ++m) { const int row = row0 + ai * HALF + m * 16;
;                     const u32x4 z = __builtin_nontemporal_load((const u32x4*)(proj + (size_t)row * NPROJ + C_ZP + col));
;                     f32x4 v0 = (acc[ai][bj][m][0] + b0) * s0, v1 = (acc[ai][bj][m][1] + b1) * s1;
;                     v0[0] *= siluf_(bflo(z.x)); v0[1] *= siluf_(bfhi(z.x)); v0[2] *= siluf_(bflo(z.y)); v0[3] *= siluf_(bfhi(z.y));
;                     v1[0] *= siluf_(bflo(z.z)); v1[1] *= siluf_(bfhi(z.z)); v1[2] *= siluf_(bflo(z.w)); v1[3] *= siluf_(bfhi(z.w));
;                     u32x4 w; w.x = pk2(v0[0], v0[1]); w.y = pk2(v0[2], v0[3]); w.z = pk2(v1[0], v1[1]); w.w = pk2(v1[2], v1[3]);
;                     *(u32x4*)(a2 + (size_t)row * 4096 + 2048 + col) = w; } }
	v_pk_mul_f32 v[34:35], v[34:35], v[66:67]
	v_pk_mul_f32 v[38:39], v[38:39], v[70:71]
	v_pk_mul_f32 v[36:37], v[36:37], v[68:69]
	v_pk_mul_f32 v[32:33], v[32:33], v[64:65]
	v_pk_add_f32 v[26:27], v[26:27], v[74:75]
	v_pk_add_f32 v[30:31], v[30:31], v[78:79]
	v_pk_add_f32 v[28:29], v[28:29], v[76:77]
	v_pk_add_f32 v[24:25], v[24:25], v[72:73]
	v_pk_mul_f32 v[26:27], v[26:27], v[66:67]
	v_pk_mul_f32 v[30:31], v[30:31], v[70:71]
	v_pk_mul_f32 v[28:29], v[28:29], v[68:69]
	v_pk_mul_f32 v[24:25], v[24:25], v[64:65]
	v_pk_add_f32 v[18:19], v[18:19], v[74:75]
	v_pk_add_f32 v[22:23], v[22:23], v[78:79]
	v_pk_add_f32 v[20:21], v[20:21], v[76:77]
	v_pk_add_f32 v[16:17], v[16:17], v[72:73]
	v_pk_mul_f32 v[18:19], v[18:19], v[66:67]
	v_pk_mul_f32 v[22:23], v[22:23], v[70:71]
	v_pk_mul_f32 v[20:21], v[20:21], v[68:69]
	v_pk_mul_f32 v[16:17], v[16:17], v[64:65]
	v_pk_add_f32 v[10:11], v[10:11], v[74:75]
	v_pk_add_f32 v[14:15], v[14:15], v[78:79]
	v_pk_add_f32 v[12:13], v[12:13], v[76:77]
	v_pk_add_f32 v[8:9], v[8:9], v[72:73]
	v_pk_mul_f32 v[10:11], v[10:11], v[66:67]
	v_pk_mul_f32 v[14:15], v[14:15], v[70:71]
	v_pk_mul_f32 v[12:13], v[12:13], v[68:69]
	v_pk_mul_f32 v[8:9], v[8:9], v[64:65]
	v_pk_add_f32 v[2:3], v[2:3], v[74:75]
	v_pk_add_f32 v[6:7], v[6:7], v[78:79]
	v_pk_add_f32 v[4:5], v[4:5], v[76:77]
	v_pk_add_f32 v[0:1], v[0:1], v[72:73]
	v_pk_mul_f32 v[2:3], v[2:3], v[66:67]
	v_pk_mul_f32 v[6:7], v[6:7], v[70:71]
	v_pk_mul_f32 v[4:5], v[4:5], v[68:69]
	v_pk_mul_f32 v[0:1], v[0:1], v[64:65]
	s_waitcnt vmcnt(1)
	v_mov_b32_e32 v56, v206
	v_mov_b32_e32 v57, v207
	v_mov_b32_e32 v58, v208
	v_mov_b32_e32 v59, v209
	v_lshlrev_b32_e32 v93, 16, v59
	v_and_b32_e32 v59, 0xffff0000, v59
	v_lshlrev_b32_e32 v86, 16, v56
	v_and_b32_e32 v56, 0xffff0000, v56
	v_lshlrev_b32_e32 v87, 16, v57
	v_and_b32_e32 v57, 0xffff0000, v57
	v_lshlrev_b32_e32 v92, 16, v58
	v_and_b32_e32 v58, 0xffff0000, v58
	v_mul_f32_e32 v109, 0xbfb8aa3b, v59
	v_mul_f32_e32 v94, 0xbfb8aa3b, v86
	v_mul_f32_e32 v95, 0xbfb8aa3b, v56
	v_mul_f32_e32 v100, 0xbfb8aa3b, v87
	v_mul_f32_e32 v101, 0xbfb8aa3b, v57
	v_mul_f32_e32 v102, 0xbfb8aa3b, v92
	v_mul_f32_e32 v103, 0xbfb8aa3b, v58
	v_mul_f32_e32 v108, 0xbfb8aa3b, v93
	v_exp_f32_e32 v109, v109
	v_exp_f32_e32 v94, v94
	v_exp_f32_e32 v95, v95
	v_exp_f32_e32 v100, v100
	v_exp_f32_e32 v101, v101
	v_exp_f32_e32 v102, v102
	v_exp_f32_e32 v103, v103
	v_exp_f32_e32 v108, v108
	v_add_f32_e32 v109, 1.0, v109
	v_add_f32_e32 v94, 1.0, v94
	v_add_f32_e32 v95, 1.0, v95
	v_add_f32_e32 v100, 1.0, v100
	v_add_f32_e32 v101, 1.0, v101
	v_add_f32_e32 v102, 1.0, v102
	v_add_f32_e32 v103, 1.0, v103
	v_add_f32_e32 v108, 1.0, v108
	v_rcp_f32_e32 v109, v109
	v_rcp_f32_e32 v94, v94
	v_rcp_f32_e32 v95, v95
	v_rcp_f32_e32 v100, v100
	v_rcp_f32_e32 v101, v101
	v_rcp_f32_e32 v102, v102
	v_rcp_f32_e32 v103, v103
	v_rcp_f32_e32 v108, v108
	v_mul_f32_e32 v59, v109, v59
	v_mul_f32_e32 v86, v94, v86
	v_mul_f32_e32 v56, v95, v56
	v_mul_f32_e32 v87, v100, v87
	v_mul_f32_e32 v57, v101, v57
	v_mul_f32_e32 v92, v102, v92
	v_mul_f32_e32 v58, v103, v58
	v_mul_f32_e32 v93, v108, v93
	v_mul_f32_e32 v51, v51, v59
	v_mul_f32_e32 v52, v52, v86
	v_mul_f32_e32 v53, v53, v56
	v_mul_f32_e32 v54, v54, v87
	v_mul_f32_e32 v55, v55, v57
	v_mul_f32_e32 v56, v48, v92
	v_mul_f32_e32 v57, v49, v58
	v_mul_f32_e32 v58, v50, v93
	v_cvt_pk_bf16_f32 v48, v52, v53
	v_cvt_pk_bf16_f32 v49, v54, v55
	v_cvt_pk_bf16_f32 v50, v56, v57
	v_cvt_pk_bf16_f32 v51, v58, v51
	global_store_dwordx4 v[62:63], v[48:51], off
	v_lshl_add_u64 v[54:55], v[114:115], 0, v[168:169]
	v_lshl_add_u64 v[52:53], v[112:113], 0, v[168:169]
	s_waitcnt vmcnt(2)
	v_mov_b32_e32 v48, v210
	v_mov_b32_e32 v49, v211
	v_mov_b32_e32 v50, v212
	v_mov_b32_e32 v51, v213
	v_lshlrev_b32_e32 v59, 16, v51
	v_and_b32_e32 v51, 0xffff0000, v51
	v_lshlrev_b32_e32 v56, 16, v48
	v_and_b32_e32 v48, 0xffff0000, v48
	v_lshlrev_b32_e32 v57, 16, v49
	v_and_b32_e32 v49, 0xffff0000, v49
	v_lshlrev_b32_e32 v58, 16, v50
	v_and_b32_e32 v50, 0xffff0000, v50
	v_mul_f32_e32 v93, 0xbfb8aa3b, v51
	v_mul_f32_e32 v60, 0xbfb8aa3b, v56
	v_mul_f32_e32 v61, 0xbfb8aa3b, v48
	v_mul_f32_e32 v62, 0xbfb8aa3b, v57
	v_mul_f32_e32 v63, 0xbfb8aa3b, v49
	v_mul_f32_e32 v86, 0xbfb8aa3b, v58
	v_mul_f32_e32 v87, 0xbfb8aa3b, v50
	v_mul_f32_e32 v92, 0xbfb8aa3b, v59
	v_exp_f32_e32 v93, v93
	v_exp_f32_e32 v60, v60
	v_exp_f32_e32 v61, v61
	v_exp_f32_e32 v62, v62
	v_exp_f32_e32 v63, v63
	v_exp_f32_e32 v86, v86
	v_exp_f32_e32 v87, v87
	v_exp_f32_e32 v92, v92
	v_add_f32_e32 v93, 1.0, v93
	v_add_f32_e32 v60, 1.0, v60
	v_add_f32_e32 v61, 1.0, v61
	v_add_f32_e32 v62, 1.0, v62
	v_add_f32_e32 v63, 1.0, v63
	v_add_f32_e32 v86, 1.0, v86
	v_add_f32_e32 v87, 1.0, v87
	v_add_f32_e32 v92, 1.0, v92
	v_rcp_f32_e32 v93, v93
	v_rcp_f32_e32 v60, v60
	v_rcp_f32_e32 v61, v61
	v_rcp_f32_e32 v62, v62
	v_rcp_f32_e32 v63, v63
	v_rcp_f32_e32 v86, v86
	v_rcp_f32_e32 v87, v87
	v_rcp_f32_e32 v92, v92
	v_mul_f32_e32 v51, v93, v51
	v_mul_f32_e32 v56, v60, v56
	v_mul_f32_e32 v48, v61, v48
	v_mul_f32_e32 v57, v62, v57
	v_mul_f32_e32 v49, v63, v49
	v_mul_f32_e32 v58, v86, v58
	v_mul_f32_e32 v50, v87, v50
	v_mul_f32_e32 v59, v92, v59
	v_mul_f32_e32 v43, v43, v51
	v_mul_f32_e32 v44, v44, v56
	v_mul_f32_e32 v45, v45, v48
	v_mul_f32_e32 v46, v46, v57
	v_mul_f32_e32 v47, v47, v49
	v_mul_f32_e32 v48, v40, v58
	v_mul_f32_e32 v49, v41, v50
	v_mul_f32_e32 v50, v42, v59
	v_cvt_pk_bf16_f32 v40, v44, v45
	v_cvt_pk_bf16_f32 v41, v46, v47
	v_cvt_pk_bf16_f32 v42, v48, v49
	v_cvt_pk_bf16_f32 v43, v50, v43
	global_store_dwordx4 v[54:55], v[40:43], off
	v_lshl_add_u64 v[46:47], v[106:107], 0, v[168:169]
	v_lshl_add_u64 v[44:45], v[104:105], 0, v[168:169]
	s_waitcnt vmcnt(3)
; __device__ __forceinline__ float bflo(unsigned w) { return __uint_as_float(w << 16); }
; __device__ __forceinline__ float bfhi(unsigned w) { return __uint_as_float(w & 0xffff0000u); }
; __device__ __forceinline__ unsigned pk2(float lo, float hi) { unsigned r; asm("v_cvt_pk_bf16_f32 %0, %1, %2" : "=v"(r) : "v"(lo), "v"(hi)); return r; }
; __device__ __forceinline__ float siluf_(float x) { return x * __builtin_amdgcn_rcpf(1.0f + __expf(-x)); }
;     __device__ __forceinline__ void operator()(const f32x4 (&acc)[2][2][4][2], const Unit& u, int wr, int wc, int fr, int fq) const {
;     ...
;             for (int ai = 0; ai < 2; ++ai)
; #pragma unroll
;                 for (int m = 0; m < 4; ++m) { const int row = row0 + ai * HALF + m * 16;
;                     const u32x4 z = __builtin_nontemporal_load((const u32x4*)(proj + (size_t)row * NPROJ + C_ZP + col));
;                     f32x4 v0 = (acc[ai][bj][m][0] + b0) * s0, v1 = (acc[ai][bj][m][1] + b1) * s1;
;                     v0[0] *= siluf_(bflo(z.x)); v0[1] *= siluf_(bfhi(z.x)); v0[2] *= siluf_(bflo(z.y)); v0[3] *= siluf_(bfhi(z.y));
;                     v1[0] *= siluf_(bflo(z.z)); v1[1] *= siluf_(bfhi(z.z)); v1[2] *= siluf_(bflo(z.w)); v1[3] *= siluf_(bfhi(z.w));
;                     u32x4 w; w.x = pk2(v0[0], v0[1]); w.y = pk2(v0[2], v0[3]); w.z = pk2(v1[0], v1[1]); w.w = pk2(v1[2], v1[3]);
;                     *(u32x4*)(a2 + (size_t)row * 4096 + 2048 + col) = w; } }
	v_mov_b32_e32 v40, v214
	v_mov_b32_e32 v41, v215
	v_mov_b32_e32 v42, v216
	v_mov_b32_e32 v43, v217
	v_lshlrev_b32_e32 v51, 16, v43
	v_and_b32_e32 v43, 0xffff0000, v43
	v_lshlrev_b32_e32 v48, 16, v40
	v_and_b32_e32 v40, 0xffff0000, v40
	v_lshlrev_b32_e32 v49, 16, v41
	v_and_b32_e32 v41, 0xffff0000, v41
	v_lshlrev_b32_e32 v50, 16, v42
	v_and_b32_e32 v42, 0xffff0000, v42
	v_mul_f32_e32 v59, 0xbfb8aa3b, v43
	v_mul_f32_e32 v52, 0xbfb8aa3b, v48
	v_mul_f32_e32 v53, 0xbfb8aa3b, v40
	v_mul_f32_e32 v54, 0xbfb8aa3b, v49
	v_mul_f32_e32 v55, 0xbfb8aa3b, v41
	v_mul_f32_e32 v56, 0xbfb8aa3b, v50
	v_mul_f32_e32 v57, 0xbfb8aa3b, v42
	v_mul_f32_e32 v58, 0xbfb8aa3b, v51
	v_exp_f32_e32 v59, v59
	v_exp_f32_e32 v52, v52
	v_exp_f32_e32 v53, v53
	v_exp_f32_e32 v54, v54
	v_exp_f32_e32 v55, v55
	v_exp_f32_e32 v56, v56
	v_exp_f32_e32 v57, v57
	v_exp_f32_e32 v58, v58
	v_add_f32_e32 v59, 1.0, v59
	v_add_f32_e32 v52, 1.0, v52
	v_add_f32_e32 v53, 1.0, v53
	v_add_f32_e32 v54, 1.0, v54
	v_add_f32_e32 v55, 1.0, v55
	v_add_f32_e32 v56, 1.0, v56
	v_add_f32_e32 v57, 1.0, v57
	v_add_f32_e32 v58, 1.0, v58
	v_rcp_f32_e32 v59, v59
	v_rcp_f32_e32 v52, v52
	v_rcp_f32_e32 v53, v53
	v_rcp_f32_e32 v54, v54
	v_rcp_f32_e32 v55, v55
	v_rcp_f32_e32 v56, v56
	v_rcp_f32_e32 v57, v57
	v_rcp_f32_e32 v58, v58
	v_mul_f32_e32 v43, v59, v43
	v_mul_f32_e32 v48, v52, v48
	v_mul_f32_e32 v40, v53, v40
	v_mul_f32_e32 v49, v54, v49
	v_mul_f32_e32 v41, v55, v41
	v_mul_f32_e32 v50, v56, v50
	v_mul_f32_e32 v42, v57, v42
	v_mul_f32_e32 v51, v58, v51
	v_mul_f32_e32 v35, v35, v43
	v_mul_f32_e32 v36, v36, v48
	v_mul_f32_e32 v37, v37, v40
	v_mul_f32_e32 v38, v38, v49
	v_mul_f32_e32 v39, v39, v41
	v_mul_f32_e32 v40, v32, v50
	v_mul_f32_e32 v41, v33, v42
	v_mul_f32_e32 v42, v34, v51
	v_cvt_pk_bf16_f32 v32, v36, v37
	v_cvt_pk_bf16_f32 v33, v38, v39
	v_cvt_pk_bf16_f32 v34, v40, v41
	v_cvt_pk_bf16_f32 v35, v42, v35
	global_store_dwordx4 v[46:47], v[32:35], off
	v_lshl_add_u64 v[38:39], v[98:99], 0, v[168:169]
	v_lshl_add_u64 v[36:37], v[96:97], 0, v[168:169]
	s_waitcnt vmcnt(4)
	v_mov_b32_e32 v32, v218
	v_mov_b32_e32 v33, v219
	v_mov_b32_e32 v34, v220
	v_mov_b32_e32 v35, v221
	v_lshlrev_b32_e32 v43, 16, v35
	v_and_b32_e32 v35, 0xffff0000, v35
	v_lshlrev_b32_e32 v40, 16, v32
	v_and_b32_e32 v32, 0xffff0000, v32
	v_lshlrev_b32_e32 v41, 16, v33
	v_and_b32_e32 v33, 0xffff0000, v33
	v_lshlrev_b32_e32 v42, 16, v34
	v_and_b32_e32 v34, 0xffff0000, v34
	v_mul_f32_e32 v51, 0xbfb8aa3b, v35
	v_mul_f32_e32 v44, 0xbfb8aa3b, v40
	v_mul_f32_e32 v45, 0xbfb8aa3b, v32
	v_mul_f32_e32 v46, 0xbfb8aa3b, v41
	v_mul_f32_e32 v47, 0xbfb8aa3b, v33
	v_mul_f32_e32 v48, 0xbfb8aa3b, v42
	v_mul_f32_e32 v49, 0xbfb8aa3b, v34
	v_mul_f32_e32 v50, 0xbfb8aa3b, v43
	v_exp_f32_e32 v51, v51
	v_exp_f32_e32 v44, v44
	v_exp_f32_e32 v45, v45
	v_exp_f32_e32 v46, v46
	v_exp_f32_e32 v47, v47
	v_exp_f32_e32 v48, v48
	v_exp_f32_e32 v49, v49
	v_exp_f32_e32 v50, v50
	v_add_f32_e32 v51, 1.0, v51
	v_add_f32_e32 v44, 1.0, v44
	v_add_f32_e32 v45, 1.0, v45
	v_add_f32_e32 v46, 1.0, v46
	v_add_f32_e32 v47, 1.0, v47
	v_add_f32_e32 v48, 1.0, v48
	v_add_f32_e32 v49, 1.0, v49
	v_add_f32_e32 v50, 1.0, v50
	v_rcp_f32_e32 v51, v51
	v_rcp_f32_e32 v44, v44
	v_rcp_f32_e32 v45, v45
	v_rcp_f32_e32 v46, v46
	v_rcp_f32_e32 v47, v47
	v_rcp_f32_e32 v48, v48
	v_rcp_f32_e32 v49, v49
	v_rcp_f32_e32 v50, v50
	v_mul_f32_e32 v35, v51, v35
	v_mul_f32_e32 v40, v44, v40
	v_mul_f32_e32 v32, v45, v32
	v_mul_f32_e32 v41, v46, v41
	v_mul_f32_e32 v33, v47, v33
	v_mul_f32_e32 v42, v48, v42
	v_mul_f32_e32 v34, v49, v34
	v_mul_f32_e32 v43, v50, v43
	v_mul_f32_e32 v27, v27, v35
	v_mul_f32_e32 v28, v28, v40
	v_mul_f32_e32 v29, v29, v32
	v_mul_f32_e32 v30, v30, v41
	v_mul_f32_e32 v31, v31, v33
	v_mul_f32_e32 v32, v24, v42
	v_mul_f32_e32 v33, v25, v34
	v_mul_f32_e32 v34, v26, v43
	v_cvt_pk_bf16_f32 v24, v28, v29
	v_cvt_pk_bf16_f32 v25, v30, v31
	v_cvt_pk_bf16_f32 v26, v32, v33
	v_cvt_pk_bf16_f32 v27, v34, v27
	global_store_dwordx4 v[38:39], v[24:27], off
	v_lshl_add_u64 v[30:31], v[90:91], 0, v[168:169]
	v_lshl_add_u64 v[28:29], v[88:89], 0, v[168:169]
	s_waitcnt vmcnt(5)
; __device__ __forceinline__ float bflo(unsigned w) { return __uint_as_float(w << 16); }
; __device__ __forceinline__ float bfhi(unsigned w) { return __uint_as_float(w & 0xffff0000u); }
; __device__ __forceinline__ unsigned pk2(float lo, float hi) { unsigned r; asm("v_cvt_pk_bf16_f32 %0, %1, %2" : "=v"(r) : "v"(lo), "v"(hi)); return r; }
; __device__ __forceinline__ float siluf_(float x) { return x * __builtin_amdgcn_rcpf(1.0f + __expf(-x)); }
; #define PG8_WAIT_V(n) asm volatile("s_waitcnt vmcnt(" #n ")" ::: "memory")
; #define PG8_BAR __builtin_amdgcn_s_barrier()
; template <class Epi>
; __device__ __forceinline__ void gemm_phase(LAS unsigned char* lds, const GemmD g, const Epi& E) {
;     ...
;     PG8_WAIT_V(0);
;     if (wr == 0) PG8_BAR;
;     __device__ __forceinline__ void operator()(const f32x4 (&acc)[2][2][4][2], const Unit& u, int wr, int wc, int fr, int fq) const {
;     ...
;             for (int ai = 0; ai < 2; ++ai)
; #pragma unroll
;                 for (int m = 0; m < 4; ++m) { const int row = row0 + ai * HALF + m * 16;
;                     const u32x4 z = __builtin_nontemporal_load((const u32x4*)(proj + (size_t)row * NPROJ + C_ZP + col));
;                     f32x4 v0 = (acc[ai][bj][m][0] + b0) * s0, v1 = (acc[ai][bj][m][1] + b1) * s1;
;                     v0[0] *= siluf_(bflo(z.x)); v0[1] *= siluf_(bfhi(z.x)); v0[2] *= siluf_(bflo(z.y)); v0[3] *= siluf_(bfhi(z.y));
;                     v1[0] *= siluf_(bflo(z.z)); v1[1] *= siluf_(bfhi(z.z)); v1[2] *= siluf_(bflo(z.w)); v1[3] *= siluf_(bfhi(z.w));
;                     u32x4 w; w.x = pk2(v0[0], v0[1]); w.y = pk2(v0[2], v0[3]); w.z = pk2(v1[0], v1[1]); w.w = pk2(v1[2], v1[3]);
;                     *(u32x4*)(a2 + (size_t)row * 4096 + 2048 + col) = w; } }
	v_mov_b32_e32 v24, v222
	v_mov_b32_e32 v25, v223
	v_mov_b32_e32 v26, v224
	v_mov_b32_e32 v27, v225
	v_lshlrev_b32_e32 v35, 16, v27
	v_and_b32_e32 v27, 0xffff0000, v27
	v_lshlrev_b32_e32 v32, 16, v24
	v_and_b32_e32 v24, 0xffff0000, v24
	v_lshlrev_b32_e32 v33, 16, v25
	v_and_b32_e32 v25, 0xffff0000, v25
	v_lshlrev_b32_e32 v34, 16, v26
	v_and_b32_e32 v26, 0xffff0000, v26
	v_mul_f32_e32 v43, 0xbfb8aa3b, v27
	v_mul_f32_e32 v36, 0xbfb8aa3b, v32
	v_mul_f32_e32 v37, 0xbfb8aa3b, v24
	v_mul_f32_e32 v38, 0xbfb8aa3b, v33
	v_mul_f32_e32 v39, 0xbfb8aa3b, v25
	v_mul_f32_e32 v40, 0xbfb8aa3b, v34
	v_mul_f32_e32 v41, 0xbfb8aa3b, v26
	v_mul_f32_e32 v42, 0xbfb8aa3b, v35
	v_exp_f32_e32 v43, v43
	v_exp_f32_e32 v36, v36
	v_exp_f32_e32 v37, v37
	v_exp_f32_e32 v38, v38
	v_exp_f32_e32 v39, v39
	v_exp_f32_e32 v40, v40
	v_exp_f32_e32 v41, v41
	v_exp_f32_e32 v42, v42
	v_add_f32_e32 v43, 1.0, v43
	v_add_f32_e32 v36, 1.0, v36
	v_add_f32_e32 v37, 1.0, v37
	v_add_f32_e32 v38, 1.0, v38
	v_add_f32_e32 v39, 1.0, v39
	v_add_f32_e32 v40, 1.0, v40
	v_add_f32_e32 v41, 1.0, v41
	v_add_f32_e32 v42, 1.0, v42
	v_rcp_f32_e32 v43, v43
	v_rcp_f32_e32 v36, v36
	v_rcp_f32_e32 v37, v37
	v_rcp_f32_e32 v38, v38
	v_rcp_f32_e32 v39, v39
	v_rcp_f32_e32 v40, v40
	v_rcp_f32_e32 v41, v41
	v_rcp_f32_e32 v42, v42
	v_mul_f32_e32 v27, v43, v27
	v_mul_f32_e32 v32, v36, v32
	v_mul_f32_e32 v24, v37, v24
	v_mul_f32_e32 v33, v38, v33
	v_mul_f32_e32 v25, v39, v25
	v_mul_f32_e32 v34, v40, v34
	v_mul_f32_e32 v26, v41, v26
	v_mul_f32_e32 v35, v42, v35
	v_mul_f32_e32 v19, v19, v27
	v_mul_f32_e32 v20, v20, v32
	v_mul_f32_e32 v21, v21, v24
	v_mul_f32_e32 v22, v22, v33
	v_mul_f32_e32 v23, v23, v25
	v_mul_f32_e32 v24, v16, v34
	v_mul_f32_e32 v25, v17, v26
	v_mul_f32_e32 v26, v18, v35
	v_cvt_pk_bf16_f32 v16, v20, v21
	v_cvt_pk_bf16_f32 v17, v22, v23
	v_cvt_pk_bf16_f32 v18, v24, v25
	v_cvt_pk_bf16_f32 v19, v26, v19
	global_store_dwordx4 v[30:31], v[16:19], off
	v_lshl_add_u64 v[22:23], v[84:85], 0, v[168:169]
	v_lshl_add_u64 v[20:21], v[82:83], 0, v[168:169]
	s_waitcnt vmcnt(6)
	v_mov_b32_e32 v16, v226
	v_mov_b32_e32 v17, v227
	v_mov_b32_e32 v18, v228
	v_mov_b32_e32 v19, v229
	v_lshlrev_b32_e32 v27, 16, v19
	v_and_b32_e32 v19, 0xffff0000, v19
	v_lshlrev_b32_e32 v24, 16, v16
	v_and_b32_e32 v16, 0xffff0000, v16
	v_lshlrev_b32_e32 v25, 16, v17
	v_and_b32_e32 v17, 0xffff0000, v17
	v_lshlrev_b32_e32 v26, 16, v18
	v_and_b32_e32 v18, 0xffff0000, v18
	v_mul_f32_e32 v35, 0xbfb8aa3b, v19
	v_mul_f32_e32 v28, 0xbfb8aa3b, v24
	v_mul_f32_e32 v29, 0xbfb8aa3b, v16
	v_mul_f32_e32 v30, 0xbfb8aa3b, v25
	v_mul_f32_e32 v31, 0xbfb8aa3b, v17
	v_mul_f32_e32 v32, 0xbfb8aa3b, v26
	v_mul_f32_e32 v33, 0xbfb8aa3b, v18
	v_mul_f32_e32 v34, 0xbfb8aa3b, v27
	v_exp_f32_e32 v35, v35
	v_exp_f32_e32 v28, v28
	v_exp_f32_e32 v29, v29
	v_exp_f32_e32 v30, v30
	v_exp_f32_e32 v31, v31
	v_exp_f32_e32 v32, v32
	v_exp_f32_e32 v33, v33
	v_exp_f32_e32 v34, v34
	v_add_f32_e32 v35, 1.0, v35
	v_add_f32_e32 v28, 1.0, v28
	v_add_f32_e32 v29, 1.0, v29
	v_add_f32_e32 v30, 1.0, v30
	v_add_f32_e32 v31, 1.0, v31
	v_add_f32_e32 v32, 1.0, v32
	v_add_f32_e32 v33, 1.0, v33
	v_add_f32_e32 v34, 1.0, v34
	v_rcp_f32_e32 v35, v35
	v_rcp_f32_e32 v28, v28
	v_rcp_f32_e32 v29, v29
	v_rcp_f32_e32 v30, v30
	v_rcp_f32_e32 v31, v31
	v_rcp_f32_e32 v32, v32
	v_rcp_f32_e32 v33, v33
	v_rcp_f32_e32 v34, v34
	v_mul_f32_e32 v19, v35, v19
	v_mul_f32_e32 v24, v28, v24
	v_mul_f32_e32 v16, v29, v16
	v_mul_f32_e32 v25, v30, v25
	v_mul_f32_e32 v17, v31, v17
	v_mul_f32_e32 v26, v32, v26
	v_mul_f32_e32 v18, v33, v18
	v_mul_f32_e32 v27, v34, v27
	v_mul_f32_e32 v11, v11, v19
	v_mul_f32_e32 v12, v12, v24
	v_mul_f32_e32 v13, v13, v16
	v_mul_f32_e32 v14, v14, v25
	v_mul_f32_e32 v15, v15, v17
	v_mul_f32_e32 v16, v8, v26
	v_mul_f32_e32 v17, v9, v18
	v_mul_f32_e32 v18, v10, v27
	v_cvt_pk_bf16_f32 v8, v12, v13
	v_cvt_pk_bf16_f32 v9, v14, v15
	v_cvt_pk_bf16_f32 v10, v16, v17
	v_cvt_pk_bf16_f32 v11, v18, v11
	global_store_dwordx4 v[22:23], v[8:11], off
	v_lshl_add_u64 v[12:13], v[80:81], 0, v[168:169]
	s_waitcnt vmcnt(7)
	v_mov_b32_e32 v8, v230
	v_mov_b32_e32 v9, v231
	v_mov_b32_e32 v10, v232
	v_mov_b32_e32 v11, v233
	v_lshlrev_b32_e32 v17, 16, v11
	v_and_b32_e32 v11, 0xffff0000, v11
	v_lshlrev_b32_e32 v14, 16, v8
	v_and_b32_e32 v8, 0xffff0000, v8
	v_lshlrev_b32_e32 v15, 16, v9
	v_and_b32_e32 v9, 0xffff0000, v9
	v_lshlrev_b32_e32 v16, 16, v10
	v_and_b32_e32 v10, 0xffff0000, v10
	v_mul_f32_e32 v25, 0xbfb8aa3b, v11
	v_mul_f32_e32 v18, 0xbfb8aa3b, v14
	v_mul_f32_e32 v19, 0xbfb8aa3b, v8
	v_mul_f32_e32 v20, 0xbfb8aa3b, v15
	v_mul_f32_e32 v21, 0xbfb8aa3b, v9
	v_mul_f32_e32 v22, 0xbfb8aa3b, v16
	v_mul_f32_e32 v23, 0xbfb8aa3b, v10
	v_mul_f32_e32 v24, 0xbfb8aa3b, v17
	v_exp_f32_e32 v25, v25
	v_exp_f32_e32 v18, v18
	v_exp_f32_e32 v19, v19
	v_exp_f32_e32 v20, v20
	v_exp_f32_e32 v21, v21
	v_exp_f32_e32 v22, v22
	v_exp_f32_e32 v23, v23
	v_exp_f32_e32 v24, v24
	v_add_f32_e32 v25, 1.0, v25
	v_add_f32_e32 v18, 1.0, v18
	v_add_f32_e32 v19, 1.0, v19
	v_add_f32_e32 v20, 1.0, v20
	v_add_f32_e32 v21, 1.0, v21
	v_add_f32_e32 v22, 1.0, v22
	v_add_f32_e32 v23, 1.0, v23
	v_add_f32_e32 v24, 1.0, v24
	v_rcp_f32_e32 v25, v25
	v_rcp_f32_e32 v18, v18
	v_rcp_f32_e32 v19, v19
	v_rcp_f32_e32 v20, v20
	v_rcp_f32_e32 v21, v21
	v_rcp_f32_e32 v22, v22
	v_rcp_f32_e32 v23, v23
	v_rcp_f32_e32 v24, v24
	v_mul_f32_e32 v11, v25, v11
	v_mul_f32_e32 v14, v18, v14
	v_mul_f32_e32 v8, v19, v8
	v_mul_f32_e32 v15, v20, v15
	v_mul_f32_e32 v9, v21, v9
	v_mul_f32_e32 v16, v22, v16
	v_mul_f32_e32 v10, v23, v10
	v_mul_f32_e32 v17, v24, v17
	v_mul_f32_e32 v3, v3, v11
	v_mul_f32_e32 v4, v4, v14
	v_mul_f32_e32 v5, v5, v8
	v_mul_f32_e32 v6, v6, v15
	v_mul_f32_e32 v7, v7, v9
	v_mul_f32_e32 v8, v0, v16
	v_mul_f32_e32 v9, v1, v10
	v_mul_f32_e32 v10, v2, v17
	v_cvt_pk_bf16_f32 v0, v4, v5
	v_cvt_pk_bf16_f32 v1, v6, v7
	v_cvt_pk_bf16_f32 v2, v8, v9
	v_cvt_pk_bf16_f32 v3, v10, v3
	global_store_dwordx4 v[12:13], v[0:3], off
	s_cbranch_vccz .LBB0_595
	s_waitcnt vmcnt(0)
	s_cmpk_gt_u32 s33, 0xff
	s_cbranch_scc1 .LBB0_604
	s_barrier

; __global__ void __launch_bounds__(512, 2) fwd_megakernel(Params p) {
;     extern __shared__ __attribute__((aligned(16))) unsigned char shm[];
	.amdhsa_kernel _Z14fwd_megakernel6Params
		.amdhsa_group_segment_fixed_size 0
		.amdhsa_private_segment_fixed_size 0
		.amdhsa_kernarg_size 440
		.amdhsa_user_sgpr_count 2
		.amdhsa_user_sgpr_dispatch_ptr 0
		.amdhsa_user_sgpr_queue_ptr 0
		.amdhsa_user_sgpr_kernarg_segment_ptr 1
		.amdhsa_user_sgpr_dispatch_id 0
		.amdhsa_user_sgpr_kernarg_preload_length 0
		.amdhsa_user_sgpr_kernarg_preload_offset 0
		.amdhsa_user_sgpr_private_segment_size 0
		.amdhsa_uses_dynamic_stack 0
		.amdhsa_enable_private_segment 0
		.amdhsa_system_sgpr_workgroup_id_x 1
		.amdhsa_system_sgpr_workgroup_id_y 0
		.amdhsa_system_sgpr_workgroup_id_z 0
		.amdhsa_system_sgpr_workgroup_info 0
		.amdhsa_system_vgpr_workitem_id 2
		.amdhsa_next_free_vgpr 256
		.amdhsa_next_free_sgpr 100
		.amdhsa_accum_offset 256
		.amdhsa_reserve_vcc 1
		.amdhsa_float_round_mode_32 0
		.amdhsa_float_round_mode_16_64 0
		.amdhsa_float_denorm_mode_32 3
		.amdhsa_float_denorm_mode_16_64 3
		.amdhsa_dx10_clamp 1
		.amdhsa_ieee_mode 1
		.amdhsa_fp16_overflow 0
		.amdhsa_tg_split 0
		.amdhsa_exception_fp_ieee_invalid_op 0
		.amdhsa_exception_fp_denorm_src 0
		.amdhsa_exception_fp_ieee_div_zero 0
		.amdhsa_exception_fp_ieee_overflow 0
		.amdhsa_exception_fp_ieee_underflow 0
		.amdhsa_exception_fp_ieee_inexact 0
		.amdhsa_exception_int_div_zero 0
	.end_amdhsa_kernel

; __global__ void __launch_bounds__(512, 2) fwd_megakernel(Params p) {
;     extern __shared__ __attribute__((aligned(16))) unsigned char shm[];
.Lfunc_end0:
	.size	_Z14fwd_megakernel6Params, .Lfunc_end0-_Z14fwd_megakernel6Params
	.set _Z14fwd_megakernel6Params.num_vgpr, 256
	.set _Z14fwd_megakernel6Params.num_agpr, 0
	.set _Z14fwd_megakernel6Params.numbered_sgpr, 100
	.set _Z14fwd_megakernel6Params.num_named_barrier, 0
	.set _Z14fwd_megakernel6Params.private_seg_size, 0
	.set _Z14fwd_megakernel6Params.uses_vcc, 1
	.set _Z14fwd_megakernel6Params.uses_flat_scratch, 0
	.set _Z14fwd_megakernel6Params.has_dyn_sized_stack, 0
	.set _Z14fwd_megakernel6Params.has_recursion, 0
	.set _Z14fwd_megakernel6Params.has_indirect_call, 0

; __global__ void __launch_bounds__(512, 2) fwd_megakernel(Params p) {
;     extern __shared__ __attribute__((aligned(16))) unsigned char shm[];
amdhsa.kernels:
  - .agpr_count:     0
    .args:
      - .offset:         0
        .size:           184
        .value_kind:     by_value
      - .offset:         184
        .size:           4
        .value_kind:     hidden_block_count_x
      - .offset:         188
        .size:           4
        .value_kind:     hidden_block_count_y
      - .offset:         192
        .size:           4
        .value_kind:     hidden_block_count_z
      - .offset:         196
        .size:           2
        .value_kind:     hidden_group_size_x
      - .offset:         198
        .size:           2
        .value_kind:     hidden_group_size_y
      - .offset:         200
        .size:           2
        .value_kind:     hidden_group_size_z
      - .offset:         202
        .size:           2
        .value_kind:     hidden_remainder_x
      - .offset:         204
        .size:           2
        .value_kind:     hidden_remainder_y
      - .offset:         206
        .size:           2
        .value_kind:     hidden_remainder_z
      - .offset:         224
        .size:           8
        .value_kind:     hidden_global_offset_x
      - .offset:         232
        .size:           8
        .value_kind:     hidden_global_offset_y
      - .offset:         240
        .size:           8
        .value_kind:     hidden_global_offset_z
      - .offset:         248
        .size:           2
        .value_kind:     hidden_grid_dims
      - .offset:         272
        .size:           8
        .value_kind:     hidden_multigrid_sync_arg
      - .offset:         304
        .size:           4
        .value_kind:     hidden_dynamic_lds_size
    .group_segment_fixed_size: 0
    .kernarg_segment_align: 8
    .kernarg_segment_size: 440
    .language:       OpenCL C
    .language_version:
      - 2
      - 0
    .max_flat_workgroup_size: 512
    .name:           _Z14fwd_megakernel6Params
    .private_segment_fixed_size: 0
    .sgpr_count:     106
    .sgpr_spill_count: 179
    .symbol:         _Z14fwd_megakernel6Params.kd
    .uniform_work_group_size: 1
    .uses_dynamic_stack: false
    .vgpr_count:     256
    .vgpr_spill_count: 0
    .wavefront_size: 64
